# retention state scan: K chunks fetched two steps ahead through two register buffers (one spilled to LDS) instead of one step
# speedup vs baseline: 1.0142x; 1.0027x over previous
; #define LAS __attribute__((address_space(3)))
; DI float ret_lg2(const Params& p, int l, int dir, int h) { return log1pf(-exp2f(p.in[12][(l * 2 + dir) * 5 + h])) * 1.4426950408889634f; }
; DI void phase_ret_scan(const Params& p, int l, LAS unsigned char* lds) {
;     ...
;         const int it = next_item(ctr, slot);
;         if (it >= 320) break;
;         const int dvb = it & 7, dir = (it >> 3) & 1, h = (it >> 4) % 5, b = it / 80, dkb = wid;
;         {
;             const bf16_t* vsrc = (const bf16_t*)(ws + WS_VTR) + ((size_t)b * 640 + h * 128 + dvb * 16) * RB;
;             u32x4 t[9];
; #pragma unroll
;             for (int i = 0; i < 9; ++i) { const int cid = tid + i * 512, rr = cid / 288, cc = cid % 288; t[i] = *(const u32x4*)(vsrc + (size_t)rr * RB + cc * 8); }
; #pragma unroll
;             for (int i = 0; i < 9; ++i) { const int cid = tid + i * 512, rr = cid / 288, cc = cid % 288; *(LAS u32x4*)(lds + rr * VRS + cc * 16) = t[i]; }
;         }
;         const float lg = ret_lg2(p, l, dir, h), gL = exp2f(lg * 128.f);
.LBB0_1082:
	s_or_b64 exec, exec, s[0:1]
	s_waitcnt vmcnt(0)
	v_mov_b32_e32 v0, s3
	s_waitcnt lgkmcnt(0)
	s_barrier
	ds_read_b32 v0, v0
	s_mov_b64 s[0:1], -1
	s_waitcnt lgkmcnt(0)
	v_cmp_lt_i32_e32 vcc, s4, v0
	v_readfirstlane_b32 s10, v0
	s_cbranch_vccnz .LBB0_1077
	s_ashr_i32 s0, s10, 4
	s_mul_hi_i32 s1, s0, 0x66666667
	s_lshr_b32 s6, s1, 31
	s_ashr_i32 s1, s1, 1
	s_add_i32 s1, s1, s6
	s_mul_i32 s1, s1, 5
	s_sub_i32 s6, s0, s1
	s_mul_hi_i32 s0, s10, 0x66666667
	s_lshr_b32 s1, s0, 31
	s_ashr_i32 s7, s0, 5
	s_add_i32 s7, s7, s1
	s_lshl_b32 s12, s6, 7
	s_mul_i32 s0, s7, 0x280
	s_ashr_i32 s13, s12, 31
	s_mul_hi_i32 s1, s7, 0x280
	s_add_u32 s0, s0, s12
	s_addc_u32 s1, s1, s13
	s_lshl_b32 s12, s10, 4
	s_and_b32 s17, s12, 0x70
	s_or_b32 s12, s0, s17
	s_mul_i32 s13, s1, 0x1200
	s_mul_hi_u32 s18, s12, 0x1200
	s_add_i32 s18, s18, s13
	s_mulk_i32 s12, 0x1200
	s_add_u32 s12, s87, s12
	s_addc_u32 s13, s91, s18
	s_bfe_u32 s10, s10, 0x10003
	v_lshl_add_u64 v[0:1], s[12:13], 0, v[44:45]
	v_lshl_add_u64 v[2:3], s[12:13], 0, v[48:49]
	v_lshl_add_u64 v[8:9], s[12:13], 0, v[52:53]
	s_mul_i32 s18, s10, 5
	v_lshl_add_u64 v[0:1], v[46:47], 1, v[0:1]
	v_lshl_add_u64 v[4:5], v[50:51], 1, v[2:3]
	v_lshl_add_u64 v[8:9], v[54:55], 1, v[8:9]
	v_lshl_add_u64 v[10:11], s[12:13], 0, v[56:57]
	s_add_i32 s18, s18, s6
	global_load_dwordx4 v[0:3], v[0:1], off
	s_nop 0
	global_load_dwordx4 v[4:7], v[4:5], off
	v_lshl_add_u64 v[10:11], v[58:59], 1, v[10:11]
	global_load_dwordx4 v[12:15], v[8:9], off
	global_load_dwordx4 v[16:19], v[10:11], off
	v_lshl_add_u64 v[8:9], s[12:13], 0, v[60:61]
	s_ashr_i32 s19, s18, 31
	v_lshl_add_u64 v[8:9], v[62:63], 1, v[8:9]
	v_lshl_add_u64 v[10:11], s[12:13], 0, v[64:65]
	s_lshl_b64 s[18:19], s[18:19], 2
	v_lshl_add_u64 v[10:11], v[66:67], 1, v[10:11]
	global_load_dwordx4 v[20:23], v[8:9], off
	global_load_dwordx4 v[24:27], v[10:11], off
	v_lshl_add_u64 v[8:9], s[12:13], 0, v[68:69]
	s_add_u32 s18, s60, s18
	v_lshl_add_u64 v[8:9], v[70:71], 1, v[8:9]
	v_lshl_add_u64 v[10:11], s[12:13], 0, v[72:73]
	s_addc_u32 s19, s61, s19
	v_lshl_add_u64 v[10:11], v[74:75], 1, v[10:11]
	global_load_dwordx4 v[28:31], v[8:9], off
	global_load_dwordx4 v[32:35], v[10:11], off
	global_load_dword v81, v41, s[18:19]
	v_lshl_add_u64 v[8:9], s[12:13], 0, v[76:77]
	v_lshl_add_u64 v[8:9], v[78:79], 1, v[8:9]
	global_load_dwordx4 v[8:11], v[8:9], off
	v_lshl_add_u64 v[166:167], v[38:39], 0, s[0:1]
	v_mad_u64_u32 v[84:85], s[0:1], v166, s2, v[42:43]
	v_mov_b32_e32 v40, v85
	v_mad_u64_u32 v[166:167], s[0:1], v167, s2, v[40:41]
	s_mul_i32 s7, s7, 5
	v_mov_b32_e32 v85, v166
	s_waitcnt vmcnt(0)
	ds_write_b128 v152, v[0:3]
	ds_write_b128 v153, v[4:7]
	ds_write_b128 v154, v[12:15]
	ds_write_b128 v155, v[16:19]
	ds_write_b128 v156, v[20:23]
	ds_write_b128 v157, v[24:27]
	ds_write_b128 v158, v[28:31]
	ds_write_b128 v159, v[32:35]
	v_cmp_gt_f32_e32 vcc, s5, v81
	s_and_b64 s[0:1], vcc, exec
	s_cselect_b32 s0, 0xffffffc0, 0
	v_cndmask_b32_e32 v0, 0, v162, vcc
	v_add_f32_e32 v0, v81, v0
	v_exp_f32_e32 v0, v0
	s_cmp_eq_u32 s10, 0
	s_cselect_b64 vcc, -1, 0
	s_add_i32 s7, s7, s6
	s_lshl_b32 s1, s7, 1
	s_or_b32 s1, s1, s10
	v_ldexp_f32 v22, v0, s0
	s_mul_hi_i32 s0, s1, 0x90000
	s_mul_i32 s1, s1, 0x90000
	v_sub_f32_e32 v6, 1.0, v22
	s_add_u32 s12, s92, s1
	v_add_f32_e32 v2, -1.0, v6
	v_frexp_mant_f32_e32 v7, v6
	v_cvt_f64_f32_e32 v[0:1], v6
	s_addc_u32 s13, s93, s0
	v_sub_f32_e32 v12, v2, v6
	v_frexp_exp_i32_f64_e32 v14, v[0:1]
	v_cmp_gt_f32_e64 s[0:1], s14, v7
	v_sub_f32_e64 v13, -v22, v2
	ds_write_b128 v160, v[8:11]
	v_add_f32_e32 v8, 1.0, v12
	v_subbrev_co_u32_e64 v14, s[0:1], 0, v14, s[0:1]
	v_add_f32_e32 v7, v13, v8
	v_sub_u32_e32 v8, 0, v14
	v_ldexp_f32 v6, v6, v8
	v_ldexp_f32 v7, v7, v8
	v_add_f32_e32 v8, -1.0, v6
	v_add_f32_e32 v9, 1.0, v6
	v_add_f32_e32 v10, 1.0, v8
	v_add_f32_e32 v11, -1.0, v9
	v_sub_f32_e32 v10, v6, v10
	v_sub_f32_e32 v6, v6, v11
	v_add_f32_e32 v6, v7, v6
	v_add_f32_e32 v15, v9, v6
	v_rcp_f32_e32 v17, v15
	v_add_f32_e32 v10, v7, v10
	v_sub_f32_e32 v7, v15, v9
	v_sub_f32_e32 v16, v6, v7
	v_add_f32_e32 v7, v8, v10
	v_mul_f32_e32 v19, v7, v17
	v_sub_f32_e32 v6, v7, v8
	v_mul_f32_e32 v8, v15, v19
	v_sub_f32_e32 v18, v10, v6
	v_fma_f32 v10, v19, v15, -v8
	v_fmac_f32_e32 v10, v19, v16
	v_add_f32_e32 v6, v8, v10
	v_sub_f32_e32 v9, v7, v6
	v_pk_add_f32 v[12:13], v[6:7], v[8:9] neg_lo:[0,1] neg_hi:[0,1]
	v_mov_b32_e32 v11, v6
	v_pk_add_f32 v[6:7], v[12:13], v[10:11] neg_lo:[0,1] neg_hi:[0,1]
	v_cmp_nlt_f32_e64 s[0:1], 1.0, v22
	v_add_f32_e32 v7, v18, v7
	v_add_f32_e32 v6, v6, v7
	v_add_f32_e32 v7, v9, v6
	v_mul_f32_e32 v18, v17, v7
	v_mul_f32_e32 v8, v15, v18
	v_fma_f32 v10, v18, v15, -v8
	v_fmac_f32_e32 v10, v18, v16
	v_sub_f32_e32 v9, v9, v7
	v_add_f32_e32 v15, v6, v9
	v_add_f32_e32 v6, v8, v10
	v_sub_f32_e32 v9, v7, v6
	v_pk_add_f32 v[12:13], v[6:7], v[8:9] neg_lo:[0,1] neg_hi:[0,1]
	v_mov_b32_e32 v11, v6
	v_pk_add_f32 v[6:7], v[12:13], v[10:11] neg_lo:[0,1] neg_hi:[0,1]
	s_lshl_b32 s10, s10, 8
	v_add_f32_e32 v7, v15, v7
	v_add_f32_e32 v6, v6, v7
	v_add_f32_e32 v7, v19, v18
	v_add_f32_e32 v6, v9, v6
	v_sub_f32_e32 v8, v7, v19
	v_mul_f32_e32 v6, v17, v6
	v_sub_f32_e32 v8, v18, v8
	v_add_f32_e32 v8, v8, v6
	v_add_f32_e32 v10, v7, v8
	v_mul_f32_e32 v11, v10, v10
	v_fmamk_f32 v6, v11, 0x3e9b6dac, v161
	v_fmaak_f32 v83, v11, v6, 0x3f2aaada
	v_cvt_f32_i32_e32 v6, v14
	v_sub_f32_e32 v7, v10, v7
	v_sub_f32_e32 v7, v8, v7
	v_ldexp_f32 v12, v7, 1
	v_mul_f32_e32 v7, v10, v11
	v_ldexp_f32 v9, v10, 1
	v_pk_mul_f32 v[10:11], v[6:7], v[82:83]
	v_lshl_add_u64 v[4:5], v[84:85], 0, s[10:11]
	v_fma_f32 v8, v6, s15, -v10
	v_fmac_f32_e32 v8, 0xb102e308, v6
	v_pk_add_f32 v[6:7], v[10:11], v[8:9]
; #define LAS __attribute__((address_space(3)))
; DI float ret_lg2(const Params& p, int l, int dir, int h) { return log1pf(-exp2f(p.in[12][(l * 2 + dir) * 5 + h])) * 1.4426950408889634f; }
; DI void phase_ret_scan(const Params& p, int l, LAS unsigned char* lds) {
;     ...
;         const float lg = ret_lg2(p, l, dir, h), gL = exp2f(lg * 128.f);
;         float wt[4][8];
; #pragma unroll
;         for (int ks = 0; ks < 4; ++ks)
; #pragma unroll
;             for (int e = 0; e < 8; ++e) { const int pp = ks * 32 + q4 * 8 + e; wt[ks][e] = exp2f(lg * (float)(dir == 0 ? 127 - pp : pp)); }
;         const bf16_t* kt = (const bf16_t*)(ws + WS_KTR) + ((size_t)b * 640 + h * 128 + dkb * 16 + r16) * RB + q4 * 8;
;         const LAS unsigned char* vl = lds + r16 * VRS + q4 * 16;
;         bf16_t* sb = (bf16_t*)(ws + WS_S) + ((size_t)((b * 5 + h) * 2 + dir) * 18) * 16384 + (dvb * 16 + r16) * 128 + dkb * 16 + q4 * 4;
;         f32x4 st = (f32x4){0.f, 0.f, 0.f, 0.f};
;         bf16x8 ca[4];
;         { const int c0 = dir == 0 ? 0 : 1;
; #pragma unroll
;           for (int ks = 0; ks < 4; ++ks) ca[ks] = *(const bf16x8*)(kt + c0 * 128 + ks * 32); }
	global_load_dwordx4 v[0:3], v[4:5], off
	v_sub_f32_e32 v9, v7, v9
	v_sub_f32_e32 v9, v11, v9
	v_add_f32_e32 v13, v12, v9
	v_mov_b32_e32 v12, v10
	v_pk_add_f32 v[10:11], v[6:7], v[10:11] neg_lo:[0,1] neg_hi:[0,1]
	v_pk_add_f32 v[14:15], v[6:7], v[12:13]
	v_mov_b32_e32 v9, v6
	v_mov_b32_e32 v11, v15
	v_pk_add_f32 v[16:17], v[8:9], v[10:11] neg_lo:[0,1] neg_hi:[0,1]
	v_pk_add_f32 v[8:9], v[8:9], v[10:11]
	v_mov_b32_e32 v20, v7
	v_pk_add_f32 v[10:11], v[8:9], v[6:7] op_sel:[1,0] op_sel_hi:[0,1] neg_lo:[0,1] neg_hi:[0,1]
	v_pk_add_f32 v[18:19], v[14:15], v[10:11] op_sel_hi:[1,0] neg_lo:[0,1] neg_hi:[0,1]
	v_mov_b32_e32 v14, v15
	v_mov_b32_e32 v15, v9
	v_mov_b32_e32 v21, v10
	v_pk_add_f32 v[10:11], v[14:15], v[20:21] neg_lo:[0,1] neg_hi:[0,1]
	v_mov_b32_e32 v12, v13
	v_mov_b32_e32 v13, v6
	v_pk_add_f32 v[6:7], v[12:13], v[10:11] neg_lo:[0,1] neg_hi:[0,1]
	v_mov_b32_e32 v18, v16
	v_pk_add_f32 v[10:11], v[18:19], v[6:7]
	v_mov_b32_e32 v17, v9
	v_pk_add_f32 v[12:13], v[10:11], v[10:11] op_sel:[0,1] op_sel_hi:[1,0]
	v_mov_b32_e32 v81, v41
	v_pk_add_f32 v[8:9], v[8:9], v[12:13] op_sel:[1,0] op_sel_hi:[0,1]
	v_mov_b32_e32 v11, v8
	v_pk_add_f32 v[14:15], v[10:11], v[16:17] neg_lo:[0,1] neg_hi:[0,1]
	v_mov_b32_e32 v7, v12
	v_sub_f32_e32 v9, v10, v14
	v_pk_add_f32 v[6:7], v[6:7], v[14:15] neg_lo:[0,1] neg_hi:[0,1]
	v_sub_f32_e32 v9, v16, v9
	v_add_f32_e32 v6, v6, v9
	v_add_f32_e32 v6, v6, v7
	v_add_f32_e32 v6, v8, v6
	v_cndmask_b32_e64 v6, v163, v6, s[0:1]
	v_cmp_neq_f32_e64 s[0:1], 1.0, v22
	s_mov_b32 s10, 0
	s_nop 0
	v_cndmask_b32_e64 v6, v164, v6, s[0:1]
	v_cmp_lt_f32_e64 s[0:1], |v22|, s16
	s_nop 1
	v_cndmask_b32_e64 v6, v6, -v22, s[0:1]
	v_mul_f32_e32 v18, 0x3fb8aa3b, v6
	v_cndmask_b32_e32 v6, v87, v89, vcc
	v_cvt_f32_ubyte0_e32 v6, v6
	v_mul_f32_e32 v7, v18, v6
	v_cmp_gt_f32_e64 s[0:1], s5, v7
	v_mul_f32_e32 v19, 0x43000000, v18
	v_mov_b32_e32 v22, 0
	v_cndmask_b32_e64 v7, 0, v162, s[0:1]
	v_fmac_f32_e32 v7, v18, v6
	v_exp_f32_e32 v6, v7
	v_cndmask_b32_e64 v7, 0, v165, s[0:1]
	v_mov_b32_e32 v23, v22
	v_mov_b32_e32 v24, v22
	v_ldexp_f32 v26, v6, v7
	v_cndmask_b32_e32 v6, v90, v91, vcc
	v_cvt_f32_ubyte0_e32 v6, v6
	v_mul_f32_e32 v7, v18, v6
	v_cmp_gt_f32_e64 s[0:1], s5, v7
	v_mov_b32_e32 v25, v22
	s_nop 0
	v_cndmask_b32_e64 v7, 0, v162, s[0:1]
	v_fmac_f32_e32 v7, v18, v6
	v_exp_f32_e32 v6, v7
	v_cndmask_b32_e32 v7, v92, v93, vcc
	v_cvt_f32_ubyte0_e32 v7, v7
	v_mul_f32_e32 v8, v18, v7
	v_cmp_gt_f32_e64 s[6:7], s5, v8
	s_nop 1
	v_cndmask_b32_e64 v8, 0, v162, s[6:7]
	v_fmac_f32_e32 v8, v18, v7
	v_exp_f32_e32 v7, v8
	v_cndmask_b32_e64 v8, 0, v165, s[0:1]
	v_ldexp_f32 v27, v6, v8
	v_cndmask_b32_e64 v6, 0, v165, s[6:7]
	v_ldexp_f32 v28, v7, v6
	v_cndmask_b32_e32 v6, v94, v95, vcc
	v_cvt_f32_ubyte0_e32 v6, v6
	v_mul_f32_e32 v7, v18, v6
	v_cmp_gt_f32_e64 s[0:1], s5, v7
	s_nop 1
	v_cndmask_b32_e64 v7, 0, v162, s[0:1]
	v_fmac_f32_e32 v7, v18, v6
	v_exp_f32_e32 v6, v7
	v_cndmask_b32_e32 v7, v96, v97, vcc
	v_cvt_f32_ubyte0_e32 v7, v7
	v_mul_f32_e32 v8, v18, v7
	v_cmp_gt_f32_e64 s[6:7], s5, v8
	s_nop 1
	v_cndmask_b32_e64 v8, 0, v162, s[6:7]
	v_fmac_f32_e32 v8, v18, v7
	v_exp_f32_e32 v7, v8
	v_cndmask_b32_e64 v8, 0, v165, s[0:1]
	v_ldexp_f32 v29, v6, v8
	v_cndmask_b32_e64 v6, 0, v165, s[6:7]
	v_ldexp_f32 v30, v7, v6
	v_cndmask_b32_e32 v6, v98, v99, vcc
	v_cvt_f32_ubyte0_e32 v6, v6
	v_mul_f32_e32 v7, v18, v6
	v_cmp_gt_f32_e64 s[0:1], s5, v7
	s_nop 1
	v_cndmask_b32_e64 v7, 0, v162, s[0:1]
	v_fmac_f32_e32 v7, v18, v6
	v_exp_f32_e32 v6, v7
	v_cndmask_b32_e32 v7, v100, v101, vcc
	v_cvt_f32_ubyte0_e32 v7, v7
	v_mul_f32_e32 v8, v18, v7
	v_cmp_gt_f32_e64 s[6:7], s5, v8
	s_nop 1
	v_cndmask_b32_e64 v8, 0, v162, s[6:7]
	v_fmac_f32_e32 v8, v18, v7
	v_exp_f32_e32 v7, v8
	v_cndmask_b32_e64 v8, 0, v165, s[0:1]
	v_ldexp_f32 v31, v6, v8
	v_cndmask_b32_e64 v6, 0, v165, s[6:7]
	v_ldexp_f32 v32, v7, v6
	v_cndmask_b32_e32 v6, v102, v103, vcc
	v_cvt_f32_ubyte0_e32 v6, v6
	v_mul_f32_e32 v7, v18, v6
	v_cmp_gt_f32_e64 s[0:1], s5, v7
	s_nop 1
	v_cndmask_b32_e64 v7, 0, v162, s[0:1]
	v_fmac_f32_e32 v7, v18, v6
	v_exp_f32_e32 v6, v7
	v_cndmask_b32_e32 v7, v104, v105, vcc
	v_cvt_f32_ubyte0_e32 v7, v7
	v_mul_f32_e32 v8, v18, v7
	v_cmp_gt_f32_e64 s[6:7], s5, v8
	s_nop 1
	v_cndmask_b32_e64 v8, 0, v162, s[6:7]
	v_fmac_f32_e32 v8, v18, v7
	v_exp_f32_e32 v7, v8
	v_cndmask_b32_e64 v8, 0, v165, s[0:1]
	v_ldexp_f32 v33, v6, v8
	v_cndmask_b32_e64 v6, 0, v165, s[6:7]
	v_ldexp_f32 v34, v7, v6
	v_cndmask_b32_e32 v6, v106, v107, vcc
	v_cvt_f32_ubyte0_e32 v6, v6
	v_mul_f32_e32 v7, v18, v6
	v_cmp_gt_f32_e64 s[0:1], s5, v7
	s_nop 1
	v_cndmask_b32_e64 v7, 0, v162, s[0:1]
	v_fmac_f32_e32 v7, v18, v6
	v_exp_f32_e32 v6, v7
	v_cndmask_b32_e32 v7, v108, v109, vcc
	v_cvt_f32_ubyte0_e32 v7, v7
	v_mul_f32_e32 v8, v18, v7
	v_cmp_gt_f32_e64 s[6:7], s5, v8
	s_nop 1
	v_cndmask_b32_e64 v8, 0, v162, s[6:7]
	v_fmac_f32_e32 v8, v18, v7
	v_exp_f32_e32 v7, v8
	v_cndmask_b32_e64 v8, 0, v165, s[0:1]
	v_ldexp_f32 v35, v6, v8
	v_cndmask_b32_e64 v6, 0, v165, s[6:7]
	v_ldexp_f32 v83, v7, v6
	v_cndmask_b32_e32 v6, v110, v111, vcc
	v_cvt_f32_ubyte0_e32 v6, v6
	v_mul_f32_e32 v7, v18, v6
	v_cmp_gt_f32_e64 s[0:1], s5, v7
	s_nop 1
	v_cndmask_b32_e64 v7, 0, v162, s[0:1]
	v_fmac_f32_e32 v7, v18, v6
	v_exp_f32_e32 v6, v7
	v_cndmask_b32_e32 v7, v112, v113, vcc
	v_cvt_f32_ubyte0_e32 v7, v7
	v_mul_f32_e32 v8, v18, v7
	v_cmp_gt_f32_e64 s[6:7], s5, v8
	s_nop 1
	v_cndmask_b32_e64 v8, 0, v162, s[6:7]
	v_fmac_f32_e32 v8, v18, v7
	v_exp_f32_e32 v7, v8
	v_cndmask_b32_e64 v8, 0, v165, s[0:1]
	v_ldexp_f32 v166, v6, v8
	v_cndmask_b32_e64 v6, 0, v165, s[6:7]
	v_ldexp_f32 v167, v7, v6
	v_cndmask_b32_e32 v6, v114, v115, vcc
	v_cvt_f32_ubyte0_e32 v6, v6
; #define LAS __attribute__((address_space(3)))
; DI void phase_ret_scan(const Params& p, int l, LAS unsigned char* lds) {
;     ...
;         float wt[4][8];
; #pragma unroll
;         for (int ks = 0; ks < 4; ++ks)
; #pragma unroll
;             for (int e = 0; e < 8; ++e) { const int pp = ks * 32 + q4 * 8 + e; wt[ks][e] = exp2f(lg * (float)(dir == 0 ? 127 - pp : pp)); }
;         const bf16_t* kt = (const bf16_t*)(ws + WS_KTR) + ((size_t)b * 640 + h * 128 + dkb * 16 + r16) * RB + q4 * 8;
;         const LAS unsigned char* vl = lds + r16 * VRS + q4 * 16;
;         bf16_t* sb = (bf16_t*)(ws + WS_S) + ((size_t)((b * 5 + h) * 2 + dir) * 18) * 16384 + (dvb * 16 + r16) * 128 + dkb * 16 + q4 * 4;
;         f32x4 st = (f32x4){0.f, 0.f, 0.f, 0.f};
;         bf16x8 ca[4];
;         { const int c0 = dir == 0 ? 0 : 1;
; #pragma unroll
;           for (int ks = 0; ks < 4; ++ks) ca[ks] = *(const bf16x8*)(kt + c0 * 128 + ks * 32); }
;         __syncthreads();
; #pragma unroll 2
;         for (int step = 0; step < 18; ++step) {
;             const int c = dir == 0 ? step : (step < 2 ? 1 - step : 19 - step);
;             const int sn = step < 17 ? step + 1 : 17;
;             const int cn = dir == 0 ? sn : (sn < 2 ? 1 - sn : 19 - sn);
;             bf16x8 na_[4];
; #pragma unroll
;             for (int ks = 0; ks < 4; ++ks) na_[ks] = *(const bf16x8*)(kt + cn * 128 + ks * 32);
	v_mul_f32_e32 v7, v18, v6
	v_cmp_gt_f32_e64 s[0:1], s5, v7
	s_nop 1
	v_cndmask_b32_e64 v7, 0, v162, s[0:1]
	v_fmac_f32_e32 v7, v18, v6
	v_exp_f32_e32 v6, v7
	v_cndmask_b32_e32 v7, v116, v117, vcc
	v_cvt_f32_ubyte0_e32 v7, v7
	v_mul_f32_e32 v8, v18, v7
	v_cmp_gt_f32_e64 s[6:7], s5, v8
	s_nop 1
	v_cndmask_b32_e64 v8, 0, v162, s[6:7]
	v_fmac_f32_e32 v8, v18, v7
	v_exp_f32_e32 v7, v8
	v_cndmask_b32_e64 v8, 0, v165, s[0:1]
	v_ldexp_f32 v168, v6, v8
	v_cndmask_b32_e64 v6, 0, v165, s[6:7]
	v_ldexp_f32 v169, v7, v6
	v_cndmask_b32_e32 v6, v118, v119, vcc
	v_cvt_f32_ubyte0_e32 v6, v6
	v_mul_f32_e32 v7, v18, v6
	v_cmp_gt_f32_e64 s[0:1], s5, v7
	s_nop 1
	v_cndmask_b32_e64 v7, 0, v162, s[0:1]
	v_fmac_f32_e32 v7, v18, v6
	v_exp_f32_e32 v6, v7
	v_cndmask_b32_e32 v7, v120, v121, vcc
	v_cvt_f32_ubyte0_e32 v7, v7
	v_mul_f32_e32 v8, v18, v7
	v_cmp_gt_f32_e64 s[6:7], s5, v8
	s_nop 1
	v_cndmask_b32_e64 v8, 0, v162, s[6:7]
	v_fmac_f32_e32 v8, v18, v7
	v_exp_f32_e32 v7, v8
	v_cndmask_b32_e64 v8, 0, v165, s[0:1]
	v_ldexp_f32 v170, v6, v8
	v_cndmask_b32_e64 v6, 0, v165, s[6:7]
	v_ldexp_f32 v171, v7, v6
	v_cndmask_b32_e32 v6, v122, v123, vcc
	v_cvt_f32_ubyte0_e32 v6, v6
	v_mul_f32_e32 v7, v18, v6
	v_cmp_gt_f32_e64 s[0:1], s5, v7
	s_nop 1
	v_cndmask_b32_e64 v7, 0, v162, s[0:1]
	v_fmac_f32_e32 v7, v18, v6
	v_exp_f32_e32 v6, v7
	v_cndmask_b32_e32 v7, v124, v125, vcc
	v_cvt_f32_ubyte0_e32 v7, v7
	v_mul_f32_e32 v8, v18, v7
	v_cmp_gt_f32_e64 s[6:7], s5, v8
	s_nop 1
	v_cndmask_b32_e64 v8, 0, v162, s[6:7]
	v_fmac_f32_e32 v8, v18, v7
	v_exp_f32_e32 v7, v8
	v_cndmask_b32_e64 v8, 0, v165, s[0:1]
	v_ldexp_f32 v172, v6, v8
	v_cndmask_b32_e64 v6, 0, v165, s[6:7]
	v_ldexp_f32 v173, v7, v6
	v_cndmask_b32_e32 v6, v126, v127, vcc
	v_cvt_f32_ubyte0_e32 v6, v6
	v_mul_f32_e32 v7, v18, v6
	v_cmp_gt_f32_e64 s[0:1], s5, v7
	s_nop 1
	v_cndmask_b32_e64 v7, 0, v162, s[0:1]
	v_fmac_f32_e32 v7, v18, v6
	v_exp_f32_e32 v6, v7
	v_cndmask_b32_e32 v7, v128, v129, vcc
	v_cvt_f32_ubyte0_e32 v7, v7
	v_mul_f32_e32 v8, v18, v7
	v_cmp_gt_f32_e64 s[6:7], s5, v8
	s_nop 1
	v_cndmask_b32_e64 v8, 0, v162, s[6:7]
	v_fmac_f32_e32 v8, v18, v7
	v_exp_f32_e32 v7, v8
	v_cndmask_b32_e64 v8, 0, v165, s[0:1]
	v_ldexp_f32 v174, v6, v8
	v_cndmask_b32_e64 v6, 0, v165, s[6:7]
	v_ldexp_f32 v175, v7, v6
	v_cndmask_b32_e32 v6, v130, v131, vcc
	v_cvt_f32_ubyte0_e32 v6, v6
	v_mul_f32_e32 v7, v18, v6
	v_cmp_gt_f32_e64 s[0:1], s5, v7
	s_nop 1
	v_cndmask_b32_e64 v7, 0, v162, s[0:1]
	v_fmac_f32_e32 v7, v18, v6
	v_exp_f32_e32 v6, v7
	v_cndmask_b32_e32 v7, v132, v133, vcc
	v_cvt_f32_ubyte0_e32 v7, v7
	v_mul_f32_e32 v8, v18, v7
	v_cmp_gt_f32_e64 s[6:7], s5, v8
	s_nop 1
	v_cndmask_b32_e64 v8, 0, v162, s[6:7]
	v_fmac_f32_e32 v8, v18, v7
	v_exp_f32_e32 v7, v8
	v_cndmask_b32_e64 v8, 0, v165, s[0:1]
	v_ldexp_f32 v176, v6, v8
	v_cndmask_b32_e64 v6, 0, v165, s[6:7]
	v_ldexp_f32 v177, v7, v6
	v_cndmask_b32_e32 v6, v134, v135, vcc
	v_cvt_f32_ubyte0_e32 v6, v6
	v_mul_f32_e32 v7, v18, v6
	v_cmp_gt_f32_e64 s[0:1], s5, v7
	s_nop 1
	v_cndmask_b32_e64 v7, 0, v162, s[0:1]
	v_fmac_f32_e32 v7, v18, v6
	v_exp_f32_e32 v6, v7
	v_cndmask_b32_e32 v7, v136, v137, vcc
	v_cvt_f32_ubyte0_e32 v7, v7
	v_mul_f32_e32 v8, v18, v7
	v_cmp_gt_f32_e64 s[6:7], s5, v8
	s_nop 1
	v_cndmask_b32_e64 v8, 0, v162, s[6:7]
	v_fmac_f32_e32 v8, v18, v7
	v_exp_f32_e32 v7, v8
	v_cndmask_b32_e64 v8, 0, v165, s[0:1]
	v_ldexp_f32 v178, v6, v8
	v_cndmask_b32_e64 v6, 0, v165, s[6:7]
	v_ldexp_f32 v179, v7, v6
	v_cndmask_b32_e32 v6, v138, v139, vcc
	v_cvt_f32_ubyte0_e32 v6, v6
	v_mul_f32_e32 v7, v18, v6
	v_cmp_gt_f32_e64 s[0:1], s5, v7
	s_nop 1
	v_cndmask_b32_e64 v7, 0, v162, s[0:1]
	v_fmac_f32_e32 v7, v18, v6
	v_exp_f32_e32 v16, v7
	global_load_dwordx4 v[12:15], v[4:5], off offset:64
	global_load_dwordx4 v[8:11], v[4:5], off offset:128
	s_nop 0
	global_load_dwordx4 v[4:7], v[4:5], off offset:192
	v_lshlrev_b32_e32 v254, 4, v202
	v_add_u32_e32 v254, 0x14000, v254
	ds_write_b128 v254, v[92:95]
	ds_write_b128 v254, v[96:99] offset:8192
	ds_write_b128 v254, v[100:103] offset:16384
	ds_write_b128 v254, v[104:107] offset:24576
	s_waitcnt lgkmcnt(0)
	s_and_b64 s[100:101], vcc, exec
	s_cselect_b32 s98, 1, 0
	s_lshl_b32 s98, s98, 8
	s_mov_b32 s99, 0
	v_lshl_add_u64 v[250:251], s[98:99], 0, v[84:85]
	global_load_dwordx4 v[92:95], v[250:251], off
	global_load_dwordx4 v[96:99], v[250:251], off offset:64
	global_load_dwordx4 v[100:103], v[250:251], off offset:128
	global_load_dwordx4 v[104:107], v[250:251], off offset:192
	s_and_b64 s[100:101], vcc, exec
	s_cselect_b32 s98, 2, 17
	s_lshl_b32 s98, s98, 8
	v_lshl_add_u64 v[250:251], s[98:99], 0, v[84:85]
	global_load_dwordx4 v[234:237], v[250:251], off
	global_load_dwordx4 v[238:241], v[250:251], off offset:64
	global_load_dwordx4 v[242:245], v[250:251], off offset:128
	global_load_dwordx4 v[246:249], v[250:251], off offset:192
	v_cndmask_b32_e64 v17, 0, v165, s[0:1]
	s_waitcnt lgkmcnt(0)
	v_ldexp_f32 v180, v16, v17
	v_cndmask_b32_e32 v16, v140, v141, vcc
	v_cvt_f32_ubyte0_e32 v16, v16
	v_mul_f32_e32 v17, v18, v16
	v_cmp_gt_f32_e64 s[0:1], s5, v17
	s_barrier
; #define LAS __attribute__((address_space(3)))
; DI void st_bf16x4(bf16_t* p, f32x4 v) { u32x2 w; w.x = cvt_pk_bf16(v[0], v[1]); w.y = cvt_pk_bf16(v[2], v[3]); *(u32x2*)p = w; }
; #define MFMA16(a, b, c) __builtin_amdgcn_mfma_f32_16x16x32_bf16((a), (b), (c), 0, 0, 0)
; DI void phase_ret_scan(const Params& p, int l, LAS unsigned char* lds) {
;     ...
;         __syncthreads();
; #pragma unroll 2
;         for (int step = 0; step < 18; ++step) {
;             const int c = dir == 0 ? step : (step < 2 ? 1 - step : 19 - step);
;             const int sn = step < 17 ? step + 1 : 17;
;             const int cn = dir == 0 ? sn : (sn < 2 ? 1 - sn : 19 - sn);
;             bf16x8 na_[4];
; #pragma unroll
;             for (int ks = 0; ks < 4; ++ks) na_[ks] = *(const bf16x8*)(kt + cn * 128 + ks * 32);
;             st_bf16x4(sb + (size_t)c * 16384, st);
;             f32x4 u = (f32x4){0.f, 0.f, 0.f, 0.f};
; #pragma unroll
;             for (int ks = 0; ks < 4; ++ks) u = MFMA16(scale_bf16x8(ca[ks], wt[ks]), *(const LAS bf16x8*)(vl + (c * 128 + ks * 32) * 2), u);
;             st = st * gL + u;
; #pragma unroll
;             for (int ks = 0; ks < 4; ++ks) ca[ks] = na_[ks];
;         }
	s_nop 0
	v_cndmask_b32_e64 v17, 0, v162, s[0:1]
	v_fmac_f32_e32 v17, v18, v16
	v_exp_f32_e32 v16, v17
	v_cndmask_b32_e32 v17, v142, v143, vcc
	v_cvt_f32_ubyte0_e32 v17, v17
	v_mul_f32_e32 v20, v18, v17
	v_cmp_gt_f32_e64 s[6:7], s5, v20
	s_nop 1
	v_cndmask_b32_e64 v20, 0, v162, s[6:7]
	v_fmac_f32_e32 v20, v18, v17
	v_exp_f32_e32 v17, v20
	v_cndmask_b32_e64 v20, 0, v165, s[0:1]
	v_ldexp_f32 v181, v16, v20
	v_cndmask_b32_e64 v16, 0, v165, s[6:7]
	v_ldexp_f32 v182, v17, v16
	v_cndmask_b32_e32 v16, v144, v145, vcc
	v_cvt_f32_ubyte0_e32 v16, v16
	v_mul_f32_e32 v17, v18, v16
	v_cmp_gt_f32_e64 s[0:1], s5, v17
	s_nop 1
	v_cndmask_b32_e64 v17, 0, v162, s[0:1]
	v_fmac_f32_e32 v17, v18, v16
	v_exp_f32_e32 v16, v17
	v_cndmask_b32_e32 v17, v146, v147, vcc
	v_cvt_f32_ubyte0_e32 v17, v17
	v_mul_f32_e32 v20, v18, v17
	v_cmp_gt_f32_e64 s[6:7], s5, v20
	s_nop 1
	v_cndmask_b32_e64 v20, 0, v162, s[6:7]
	v_fmac_f32_e32 v20, v18, v17
	v_exp_f32_e32 v17, v20
	v_cndmask_b32_e64 v20, 0, v165, s[0:1]
	v_ldexp_f32 v183, v16, v20
	v_cndmask_b32_e64 v16, 0, v165, s[6:7]
	v_ldexp_f32 v184, v17, v16
	v_cndmask_b32_e32 v16, v148, v149, vcc
	v_cvt_f32_ubyte0_e32 v16, v16
	v_mul_f32_e32 v17, v18, v16
	v_cmp_gt_f32_e64 s[0:1], s5, v17
	s_nop 1
	v_cndmask_b32_e64 v17, 0, v162, s[0:1]
	v_fmac_f32_e32 v17, v18, v16
	v_exp_f32_e32 v16, v17
	v_cndmask_b32_e32 v17, v150, v151, vcc
	v_cvt_f32_ubyte0_e32 v17, v17
	v_mul_f32_e32 v20, v18, v17
	v_cmp_gt_f32_e64 s[6:7], s5, v20
	s_nop 1
	v_cndmask_b32_e64 v20, 0, v162, s[6:7]
	v_fmac_f32_e32 v20, v18, v17
	v_exp_f32_e32 v17, v20
	v_cndmask_b32_e64 v20, 0, v165, s[0:1]
	v_cmp_gt_f32_e64 s[0:1], s5, v19
	v_ldexp_f32 v185, v16, v20
	v_cndmask_b32_e64 v16, 0, v165, s[6:7]
	v_cndmask_b32_e64 v19, 0, v162, s[0:1]
	v_fmac_f32_e32 v19, 0x43000000, v18
	v_exp_f32_e32 v18, v19
	v_ldexp_f32 v186, v17, v16
	v_or_b32_e32 v16, s17, v86
	v_lshlrev_b32_e32 v40, 8, v16
	s_and_b64 s[0:1], s[0:1], exec
	v_lshl_add_u64 v[16:17], s[12:13], 0, v[40:41]
	s_cselect_b32 s0, 0xffffffc0, 0
	v_lshl_add_u64 v[16:17], v[36:37], 1, v[16:17]
	v_ldexp_f32 v18, v18, s0
	v_lshl_add_u64 v[16:17], v[16:17], 0, v[80:81]
	v_mov_b32_e32 v20, v18
	v_mov_b32_e32 v21, v18
	s_mov_b32 s0, 0
	s_waitcnt vmcnt(8)
.LBB0_1084:
	s_cmp_eq_u32 s10, 0
	s_cselect_b32 s1, 1, 19
	s_add_i32 s1, s1, s10
	s_or_b32 s12, s0, 1
	s_add_i32 s13, s1, -1
	s_and_b64 s[6:7], vcc, exec
	s_cselect_b32 s6, s12, s13
	s_lshl_b32 s12, s6, 7
	v_lshlrev_b32_e32 v40, 16, v0
	v_and_b32_e32 v0, 0xffff0000, v0
	v_lshlrev_b32_e32 v81, 16, v1
	v_and_b32_e32 v1, 0xffff0000, v1
	s_ashr_i32 s13, s12, 31
	v_lshlrev_b32_e32 v188, 16, v3
	v_lshlrev_b32_e32 v189, 16, v12
	v_lshlrev_b32_e32 v190, 16, v13
	v_lshlrev_b32_e32 v191, 16, v14
	v_lshlrev_b32_e32 v192, 16, v15
	v_lshlrev_b32_e32 v193, 16, v8
	v_lshlrev_b32_e32 v194, 16, v9
	v_lshlrev_b32_e32 v195, 16, v10
	v_lshlrev_b32_e32 v196, 16, v11
	v_lshlrev_b32_e32 v197, 16, v4
	v_lshlrev_b32_e32 v198, 16, v5
	v_lshlrev_b32_e32 v199, 16, v6
	v_mul_f32_e32 v201, v27, v0
	v_mul_f32_e32 v203, v29, v1
	v_lshl_add_u64 v[0:1], s[12:13], 1, v[84:85]
	v_mul_f32_e32 v209, v32, v188
	v_mul_f32_e32 v211, v34, v189
	v_mul_f32_e32 v212, v83, v190
	v_mul_f32_e32 v213, v167, v191
	v_mul_f32_e32 v214, v169, v192
	v_mul_f32_e32 v215, v171, v193
	v_mul_f32_e32 v217, v173, v194
	v_mul_f32_e32 v219, v175, v195
	v_mul_f32_e32 v221, v177, v196
	v_mul_f32_e32 v223, v179, v197
	v_mul_f32_e32 v225, v181, v198
	v_mul_f32_e32 v227, v183, v199
	s_and_b64 s[12:13], vcc, exec
	s_cselect_b32 s12, s0, s1
	s_ashr_i32 s13, s12, 31
	v_lshlrev_b32_e32 v187, 16, v2
	v_and_b32_e32 v2, 0xffff0000, v2
	v_and_b32_e32 v3, 0xffff0000, v3
	s_cmp_eq_u32 s0, 0
	s_cbranch_scc1 sc0_a
	s_waitcnt vmcnt(6)
	s_branch sc0_b
sc0_a:
	s_waitcnt vmcnt(4)
sc0_b:
	v_mov_b32_e32 v188, v92
	v_mov_b32_e32 v189, v93
	v_mov_b32_e32 v190, v94
	v_mov_b32_e32 v191, v95
	v_mov_b32_e32 v192, v96
	v_mov_b32_e32 v193, v97
	v_mov_b32_e32 v194, v98
	v_mov_b32_e32 v195, v99
	v_mov_b32_e32 v196, v100
	v_mov_b32_e32 v197, v101
	v_mov_b32_e32 v198, v102
	v_mov_b32_e32 v199, v103
	v_mov_b32_e32 v204, v104
	v_mov_b32_e32 v205, v105
	v_mov_b32_e32 v206, v106
	v_mov_b32_e32 v207, v107
	s_add_u32 s98, s0, 3
	s_min_u32 s98, s98, 17
	s_sub_u32 s99, 19, s98
	s_and_b64 s[100:101], vcc, exec
	s_cselect_b32 s98, s98, s99
	s_lshl_b32 s98, s98, 8
	s_mov_b32 s99, 0
	v_lshl_add_u64 v[250:251], s[98:99], 0, v[84:85]
	global_load_dwordx4 v[92:95], v[250:251], off
	global_load_dwordx4 v[96:99], v[250:251], off offset:64
	global_load_dwordx4 v[100:103], v[250:251], off offset:128
	global_load_dwordx4 v[104:107], v[250:251], off offset:192
	v_lshl_add_u32 v231, s12, 8, v88
	s_lshl_b64 s[12:13], s[12:13], 15
	v_and_b32_e32 v4, 0xffff0000, v4
	v_and_b32_e32 v5, 0xffff0000, v5
	v_and_b32_e32 v6, 0xffff0000, v6
	v_lshlrev_b32_e32 v200, 16, v7
	v_and_b32_e32 v7, 0xffff0000, v7
	v_mul_f32_e32 v208, v31, v2
	v_mul_f32_e32 v210, v33, v3
	v_cvt_pk_bf16_f32 v0, v22, v23
	v_cvt_pk_bf16_f32 v1, v24, v25
	v_lshl_add_u64 v[2:3], v[16:17], 0, s[12:13]
	v_mul_f32_e32 v40, v26, v40
	v_mul_f32_e32 v81, v28, v81
	v_mul_f32_e32 v187, v30, v187
	v_mul_f32_e32 v224, v180, v4
	v_mul_f32_e32 v226, v182, v5
	v_mul_f32_e32 v228, v184, v6
	v_mul_f32_e32 v229, v186, v7
	global_store_dwordx2 v[2:3], v[0:1], off
	v_cvt_pk_bf16_f32 v0, v40, v201
	v_cvt_pk_bf16_f32 v1, v81, v203
	v_cvt_pk_bf16_f32 v2, v187, v208
	v_cvt_pk_bf16_f32 v3, v209, v210
	ds_read_b128 v[4:7], v231
	v_and_b32_e32 v12, 0xffff0000, v12
	v_and_b32_e32 v13, 0xffff0000, v13
	v_and_b32_e32 v14, 0xffff0000, v14
	v_and_b32_e32 v15, 0xffff0000, v15
	s_add_i32 s1, s0, 2
	v_and_b32_e32 v8, 0xffff0000, v8
	v_and_b32_e32 v9, 0xffff0000, v9
	v_and_b32_e32 v10, 0xffff0000, v10
	v_and_b32_e32 v11, 0xffff0000, v11
	v_mul_f32_e32 v12, v35, v12
	v_mul_f32_e32 v13, v166, v13
	v_mul_f32_e32 v14, v168, v14
	v_mul_f32_e32 v15, v170, v15
	s_cmp_lg_u32 s0, 16
	v_mul_f32_e32 v216, v172, v8
	v_mul_f32_e32 v218, v174, v9
	v_mul_f32_e32 v220, v176, v10
	v_mul_f32_e32 v222, v178, v11
	v_cvt_pk_bf16_f32 v8, v211, v12
	v_cvt_pk_bf16_f32 v9, v212, v13
	v_cvt_pk_bf16_f32 v10, v213, v14
	v_cvt_pk_bf16_f32 v11, v214, v15
	ds_read_b128 v[12:15], v231 offset:64
	s_cselect_b32 s0, s1, 17
	s_cmp_gt_u32 s0, 1
	s_waitcnt lgkmcnt(1)
; #define LAS __attribute__((address_space(3)))
; DI void st_bf16x4(bf16_t* p, f32x4 v) { u32x2 w; w.x = cvt_pk_bf16(v[0], v[1]); w.y = cvt_pk_bf16(v[2], v[3]); *(u32x2*)p = w; }
; #define MFMA16(a, b, c) __builtin_amdgcn_mfma_f32_16x16x32_bf16((a), (b), (c), 0, 0, 0)
; DI void phase_ret_scan(const Params& p, int l, LAS unsigned char* lds) {
;     ...
; #pragma unroll 2
;         for (int step = 0; step < 18; ++step) {
;             const int c = dir == 0 ? step : (step < 2 ? 1 - step : 19 - step);
;             const int sn = step < 17 ? step + 1 : 17;
;             const int cn = dir == 0 ? sn : (sn < 2 ? 1 - sn : 19 - sn);
;             bf16x8 na_[4];
; #pragma unroll
;             for (int ks = 0; ks < 4; ++ks) na_[ks] = *(const bf16x8*)(kt + cn * 128 + ks * 32);
;             st_bf16x4(sb + (size_t)c * 16384, st);
;             f32x4 u = (f32x4){0.f, 0.f, 0.f, 0.f};
; #pragma unroll
;             for (int ks = 0; ks < 4; ++ks) u = MFMA16(scale_bf16x8(ca[ks], wt[ks]), *(const LAS bf16x8*)(vl + (c * 128 + ks * 32) * 2), u);
;             st = st * gL + u;
; #pragma unroll
;             for (int ks = 0; ks < 4; ++ks) ca[ks] = na_[ks];
;         }
;     }
	v_mfma_f32_16x16x32_bf16 v[0:3], v[0:3], v[4:7], 0
	s_cselect_b32 s7, 19, 1
	s_sub_i32 s7, s7, s0
	v_cvt_pk_bf16_f32 v208, v215, v216
	v_cvt_pk_bf16_f32 v209, v217, v218
	v_cvt_pk_bf16_f32 v210, v219, v220
	v_cvt_pk_bf16_f32 v211, v221, v222
	ds_read_b128 v[212:215], v231 offset:128
	s_and_b64 s[12:13], vcc, exec
	s_cselect_b32 s0, s0, s7
	s_waitcnt lgkmcnt(1)
	v_mfma_f32_16x16x32_bf16 v[4:7], v[8:11], v[12:15], v[0:3]
	s_lshl_b32 s12, s0, 7
	s_ashr_i32 s13, s12, 31
	v_cvt_pk_bf16_f32 v216, v223, v224
	v_cvt_pk_bf16_f32 v217, v225, v226
	v_lshl_add_u64 v[224:225], s[12:13], 1, v[84:85]
	v_mul_f32_e32 v200, v185, v200
	v_cvt_pk_bf16_f32 v218, v227, v228
	v_cvt_pk_bf16_f32 v219, v200, v229
	ds_read_b128 v[220:223], v231 offset:192
	s_waitcnt lgkmcnt(1)
	v_mfma_f32_16x16x32_bf16 v[208:211], v[208:211], v[212:215], v[4:7]
	s_nop 0
	s_nop 3
	s_cmp_eq_u32 s1, 2
	s_cbranch_scc1 sc0_c
	s_waitcnt vmcnt(6)
	s_branch sc0_d
sc0_c:
	s_waitcnt vmcnt(5)
sc0_d:
	v_mov_b32_e32 v0, v234
	v_mov_b32_e32 v1, v235
	v_mov_b32_e32 v2, v236
	v_mov_b32_e32 v3, v237
	v_mov_b32_e32 v12, v238
	v_mov_b32_e32 v13, v239
	v_mov_b32_e32 v14, v240
	v_mov_b32_e32 v15, v241
	v_mov_b32_e32 v8, v242
	v_mov_b32_e32 v9, v243
	v_mov_b32_e32 v10, v244
	v_mov_b32_e32 v11, v245
	v_mov_b32_e32 v4, v246
	v_mov_b32_e32 v5, v247
	v_mov_b32_e32 v6, v248
	v_mov_b32_e32 v7, v249
	s_add_u32 s98, s1, 2
	s_min_u32 s98, s98, 17
	s_sub_u32 s99, 19, s98
	s_and_b64 s[100:101], vcc, exec
	s_cselect_b32 s98, s98, s99
	s_lshl_b32 s98, s98, 8
	s_mov_b32 s99, 0
	v_lshl_add_u64 v[250:251], s[98:99], 0, v[84:85]
	global_load_dwordx4 v[234:237], v[250:251], off
	global_load_dwordx4 v[238:241], v[250:251], off offset:64
	global_load_dwordx4 v[242:245], v[250:251], off offset:128
	global_load_dwordx4 v[246:249], v[250:251], off offset:192
	s_ashr_i32 s7, s6, 31
	v_mov_b32_e32 v19, v18
	s_waitcnt lgkmcnt(0)
	v_mfma_f32_16x16x32_bf16 v[208:211], v[216:219], v[220:223], v[208:211]
	v_lshl_add_u32 v230, s6, 8, v88
	s_lshl_b64 s[6:7], s[6:7], 15
	v_lshl_add_u64 v[200:201], v[16:17], 0, s[6:7]
	v_lshlrev_b32_e32 v40, 16, v190
	v_and_b32_e32 v81, 0xffff0000, v190
	s_nop 1
	v_pk_fma_f32 v[212:213], v[18:19], v[24:25], v[210:211]
	v_pk_fma_f32 v[214:215], v[20:21], v[22:23], v[208:209]
	v_lshlrev_b32_e32 v24, 16, v189
	v_cvt_pk_bf16_f32 v22, v214, v215
	v_cvt_pk_bf16_f32 v23, v212, v213
	global_store_dwordx2 v[200:201], v[22:23], off
	v_lshlrev_b32_e32 v22, 16, v188
	v_and_b32_e32 v23, 0xffff0000, v188
	v_and_b32_e32 v25, 0xffff0000, v189
	v_and_b32_e32 v188, 0xffff0000, v191
	v_lshlrev_b32_e32 v187, 16, v191
	v_lshlrev_b32_e32 v189, 16, v192
	v_and_b32_e32 v190, 0xffff0000, v192
	v_lshlrev_b32_e32 v191, 16, v193
	v_mul_f32_e32 v22, v26, v22
	v_mul_f32_e32 v23, v27, v23
	v_mul_f32_e32 v24, v28, v24
	v_mul_f32_e32 v25, v29, v25
	v_mul_f32_e32 v188, v33, v188
	v_mul_f32_e32 v40, v30, v40
	v_mul_f32_e32 v81, v31, v81
	v_mul_f32_e32 v187, v32, v187
	v_mul_f32_e32 v218, v34, v189
	v_mul_f32_e32 v219, v35, v190
	v_mul_f32_e32 v220, v83, v191
	v_cvt_pk_bf16_f32 v22, v22, v23
	v_cvt_pk_bf16_f32 v23, v24, v25
	v_cvt_pk_bf16_f32 v24, v40, v81
	v_cvt_pk_bf16_f32 v25, v187, v188
	ds_read_b128 v[188:191], v230
	v_and_b32_e32 v192, 0xffff0000, v193
	v_lshlrev_b32_e32 v193, 16, v194
	v_and_b32_e32 v194, 0xffff0000, v194
	v_lshlrev_b32_e32 v200, 16, v195
	v_and_b32_e32 v195, 0xffff0000, v195
	v_lshlrev_b32_e32 v201, 16, v196
	v_and_b32_e32 v196, 0xffff0000, v196
	v_lshlrev_b32_e32 v203, 16, v197
	v_and_b32_e32 v197, 0xffff0000, v197
	v_lshlrev_b32_e32 v208, 16, v198
	v_and_b32_e32 v198, 0xffff0000, v198
	v_lshlrev_b32_e32 v209, 16, v199
	v_and_b32_e32 v199, 0xffff0000, v199
	v_mul_f32_e32 v194, v168, v194
	v_mul_f32_e32 v195, v170, v195
	v_mul_f32_e32 v221, v166, v192
	v_mul_f32_e32 v222, v167, v193
	v_mul_f32_e32 v200, v169, v200
	v_mul_f32_e32 v223, v172, v196
	v_mul_f32_e32 v224, v174, v197
	v_mul_f32_e32 v225, v176, v198
	v_mul_f32_e32 v226, v178, v199
	v_cvt_pk_bf16_f32 v192, v218, v219
	v_cvt_pk_bf16_f32 v193, v220, v221
	v_cvt_pk_bf16_f32 v194, v222, v194
	v_cvt_pk_bf16_f32 v195, v200, v195
	ds_read_b128 v[196:199], v230 offset:64
	s_waitcnt lgkmcnt(1)
	v_mfma_f32_16x16x32_bf16 v[22:25], v[22:25], v[188:191], 0
	v_lshlrev_b32_e32 v210, 16, v204
	v_and_b32_e32 v204, 0xffff0000, v204
	v_lshlrev_b32_e32 v211, 16, v205
	v_and_b32_e32 v205, 0xffff0000, v205
	v_lshlrev_b32_e32 v216, 16, v206
	v_and_b32_e32 v206, 0xffff0000, v206
	v_lshlrev_b32_e32 v217, 16, v207
	v_and_b32_e32 v207, 0xffff0000, v207
	v_mul_f32_e32 v201, v171, v201
	v_mul_f32_e32 v203, v173, v203
	v_mul_f32_e32 v208, v175, v208
	v_mul_f32_e32 v209, v177, v209
	v_mul_f32_e32 v227, v180, v204
	v_mul_f32_e32 v228, v182, v205
	v_mul_f32_e32 v229, v184, v206
	v_mul_f32_e32 v231, v186, v207
	v_cvt_pk_bf16_f32 v204, v201, v223
	v_cvt_pk_bf16_f32 v205, v203, v224
	v_cvt_pk_bf16_f32 v206, v208, v225
	v_cvt_pk_bf16_f32 v207, v209, v226
	ds_read_b128 v[188:191], v230 offset:128
	s_waitcnt lgkmcnt(1)
	v_mfma_f32_16x16x32_bf16 v[22:25], v[192:195], v[196:199], v[22:25]
	v_mul_f32_e32 v210, v179, v210
	v_mul_f32_e32 v211, v181, v211
	v_mul_f32_e32 v216, v183, v216
	v_mul_f32_e32 v217, v185, v217
	v_cvt_pk_bf16_f32 v208, v210, v227
	v_cvt_pk_bf16_f32 v209, v211, v228
	v_cvt_pk_bf16_f32 v210, v216, v229
	v_cvt_pk_bf16_f32 v211, v217, v231
	s_waitcnt lgkmcnt(0)
	v_mfma_f32_16x16x32_bf16 v[22:25], v[204:207], v[188:191], v[22:25]
	ds_read_b128 v[188:191], v230 offset:192
	s_add_i32 s10, s10, -2
	s_mov_b32 s0, s1
	s_waitcnt lgkmcnt(0)
	v_mfma_f32_16x16x32_bf16 v[22:25], v[208:211], v[188:191], v[22:25]
	s_cmp_eq_u32 s1, 18
	s_nop 6
	v_pk_fma_f32 v[24:25], v[18:19], v[212:213], v[24:25]
	v_pk_fma_f32 v[22:23], v[20:21], v[214:215], v[22:23]
	s_cbranch_scc0 .LBB0_1084
	s_waitcnt vmcnt(0)
	v_lshlrev_b32_e32 v254, 4, v202
	v_add_u32_e32 v254, 0x14000, v254
	ds_read_b128 v[92:95], v254
	ds_read_b128 v[96:99], v254 offset:8192
	ds_read_b128 v[100:103], v254 offset:16384
	ds_read_b128 v[104:107], v254 offset:24576
	s_waitcnt lgkmcnt(0)
	s_mov_b64 s[0:1], 0
	s_branch .LBB0_1077

; #define LAS __attribute__((address_space(3)))
; DI float ret_lg2(const Params& p, int l, int dir, int h) { return log1pf(-exp2f(p.in[12][(l * 2 + dir) * 5 + h])) * 1.4426950408889634f; }
; DI void phase_ret_scan(const Params& p, int l, LAS unsigned char* lds) {
;     ...
;         const int it = next_item(ctr, slot);
;         if (it >= 320) break;
;         const int dvb = it & 7, dir = (it >> 3) & 1, h = (it >> 4) % 5, b = it / 80, dkb = wid;
;         {
;             const bf16_t* vsrc = (const bf16_t*)(ws + WS_VTR) + ((size_t)b * 640 + h * 128 + dvb * 16) * RB;
;             u32x4 t[9];
; #pragma unroll
;             for (int i = 0; i < 9; ++i) { const int cid = tid + i * 512, rr = cid / 288, cc = cid % 288; t[i] = *(const u32x4*)(vsrc + (size_t)rr * RB + cc * 8); }
; #pragma unroll
;             for (int i = 0; i < 9; ++i) { const int cid = tid + i * 512, rr = cid / 288, cc = cid % 288; *(LAS u32x4*)(lds + rr * VRS + cc * 16) = t[i]; }
;         }
;         const float lg = ret_lg2(p, l, dir, h), gL = exp2f(lg * 128.f);
.LBB0_2529:
	s_or_b64 exec, exec, s[0:1]
	s_waitcnt vmcnt(0)
	v_mov_b32_e32 v0, s7
	s_waitcnt lgkmcnt(0)
	s_barrier
	ds_read_b32 v0, v0
	s_mov_b64 s[0:1], -1
	s_waitcnt lgkmcnt(0)
	v_cmp_lt_i32_e32 vcc, s12, v0
	v_readfirstlane_b32 s8, v0
	s_cbranch_vccnz .LBB0_2524
	s_ashr_i32 s0, s8, 4
	s_mul_hi_i32 s1, s0, 0x66666667
	s_lshr_b32 s2, s1, 31
	s_ashr_i32 s1, s1, 1
	s_add_i32 s1, s1, s2
	s_mul_i32 s1, s1, 5
	s_sub_i32 s2, s0, s1
	s_mul_hi_i32 s0, s8, 0x66666667
	s_lshr_b32 s1, s0, 31
	s_ashr_i32 s3, s0, 5
	s_add_i32 s3, s3, s1
	s_lshl_b32 s10, s2, 7
	s_mul_i32 s0, s3, 0x280
	s_ashr_i32 s11, s10, 31
	s_mul_hi_i32 s1, s3, 0x280
	s_add_u32 s0, s0, s10
	s_addc_u32 s1, s1, s11
	s_lshl_b32 s10, s8, 4
	s_and_b32 s17, s10, 0x70
	s_or_b32 s10, s0, s17
	s_mul_i32 s11, s1, 0x1200
	s_mul_hi_u32 s18, s10, 0x1200
	s_add_i32 s18, s18, s11
	s_mulk_i32 s10, 0x1200
	s_add_u32 s10, s87, s10
	s_addc_u32 s11, s91, s18
	s_bfe_u32 s18, s8, 0x10003
	v_lshl_add_u64 v[0:1], s[10:11], 0, v[44:45]
	v_lshl_add_u64 v[2:3], s[10:11], 0, v[48:49]
	v_lshl_add_u64 v[8:9], s[10:11], 0, v[52:53]
	s_mul_i32 s8, s18, 5
	v_lshl_add_u64 v[0:1], v[46:47], 1, v[0:1]
	v_lshl_add_u64 v[4:5], v[50:51], 1, v[2:3]
	v_lshl_add_u64 v[8:9], v[54:55], 1, v[8:9]
	v_lshl_add_u64 v[10:11], s[10:11], 0, v[56:57]
	s_add_i32 s8, s2, s8
	global_load_dwordx4 v[0:3], v[0:1], off
	s_nop 0
	global_load_dwordx4 v[4:7], v[4:5], off
	v_lshl_add_u64 v[10:11], v[58:59], 1, v[10:11]
	global_load_dwordx4 v[12:15], v[8:9], off
	global_load_dwordx4 v[16:19], v[10:11], off
	v_lshl_add_u64 v[8:9], s[10:11], 0, v[60:61]
	s_add_i32 s8, s8, 10
	v_lshl_add_u64 v[8:9], v[62:63], 1, v[8:9]
	v_lshl_add_u64 v[10:11], s[10:11], 0, v[64:65]
	s_lshl_b64 s[20:21], s[8:9], 2
	v_lshl_add_u64 v[10:11], v[66:67], 1, v[10:11]
	global_load_dwordx4 v[20:23], v[8:9], off
	global_load_dwordx4 v[24:27], v[10:11], off
	v_lshl_add_u64 v[8:9], s[10:11], 0, v[68:69]
	s_add_u32 s20, s60, s20
	v_lshl_add_u64 v[8:9], v[70:71], 1, v[8:9]
	v_lshl_add_u64 v[10:11], s[10:11], 0, v[72:73]
	s_addc_u32 s21, s61, s21
	v_lshl_add_u64 v[10:11], v[74:75], 1, v[10:11]
	global_load_dwordx4 v[28:31], v[8:9], off
	global_load_dwordx4 v[32:35], v[10:11], off
	global_load_dword v81, v41, s[20:21]
	v_lshl_add_u64 v[8:9], s[10:11], 0, v[76:77]
	v_lshl_add_u64 v[8:9], v[78:79], 1, v[8:9]
	global_load_dwordx4 v[8:11], v[8:9], off
	v_lshl_add_u64 v[166:167], v[38:39], 0, s[0:1]
	v_mad_u64_u32 v[84:85], s[0:1], v166, s6, v[42:43]
	v_mov_b32_e32 v40, v85
	v_mad_u64_u32 v[166:167], s[0:1], v167, s6, v[40:41]
	s_mul_i32 s3, s3, 5
	v_mov_b32_e32 v85, v166
	s_waitcnt vmcnt(0)
	ds_write_b128 v152, v[0:3]
	ds_write_b128 v153, v[4:7]
	ds_write_b128 v154, v[12:15]
	ds_write_b128 v155, v[16:19]
	ds_write_b128 v156, v[20:23]
	ds_write_b128 v157, v[24:27]
	ds_write_b128 v158, v[28:31]
	ds_write_b128 v159, v[32:35]
	v_cmp_gt_f32_e32 vcc, s13, v81
	s_and_b64 s[0:1], vcc, exec
	s_cselect_b32 s0, 0xffffffc0, 0
	v_cndmask_b32_e32 v0, 0, v162, vcc
	v_add_f32_e32 v0, v81, v0
	v_exp_f32_e32 v0, v0
	s_cmp_eq_u32 s18, 0
	s_cselect_b64 vcc, -1, 0
	s_add_i32 s3, s3, s2
	s_lshl_b32 s1, s3, 1
	s_or_b32 s1, s1, s18
	v_ldexp_f32 v22, v0, s0
	s_mul_hi_i32 s0, s1, 0x90000
	s_mul_i32 s1, s1, 0x90000
	v_sub_f32_e32 v6, 1.0, v22
	s_add_u32 s10, s92, s1
	v_add_f32_e32 v2, -1.0, v6
	v_frexp_mant_f32_e32 v7, v6
	v_cvt_f64_f32_e32 v[0:1], v6
	s_addc_u32 s11, s93, s0
	v_sub_f32_e32 v12, v2, v6
	v_frexp_exp_i32_f64_e32 v14, v[0:1]
	v_cmp_gt_f32_e64 s[0:1], s14, v7
	v_sub_f32_e64 v13, -v22, v2
	ds_write_b128 v160, v[8:11]
	v_add_f32_e32 v8, 1.0, v12
	v_subbrev_co_u32_e64 v14, s[0:1], 0, v14, s[0:1]
	v_add_f32_e32 v7, v13, v8
	v_sub_u32_e32 v8, 0, v14
	v_ldexp_f32 v6, v6, v8
	v_ldexp_f32 v7, v7, v8
	v_add_f32_e32 v8, -1.0, v6
	v_add_f32_e32 v9, 1.0, v6
	v_add_f32_e32 v10, 1.0, v8
	v_add_f32_e32 v11, -1.0, v9
	v_sub_f32_e32 v10, v6, v10
	v_sub_f32_e32 v6, v6, v11
	v_add_f32_e32 v6, v7, v6
	v_add_f32_e32 v15, v9, v6
	v_rcp_f32_e32 v17, v15
	v_add_f32_e32 v10, v7, v10
	v_sub_f32_e32 v7, v15, v9
	v_sub_f32_e32 v16, v6, v7
	v_add_f32_e32 v7, v8, v10
	v_mul_f32_e32 v19, v7, v17
	v_sub_f32_e32 v6, v7, v8
	v_mul_f32_e32 v8, v15, v19
	v_sub_f32_e32 v18, v10, v6
	v_fma_f32 v10, v19, v15, -v8
	v_fmac_f32_e32 v10, v19, v16
	v_add_f32_e32 v6, v8, v10
	v_sub_f32_e32 v9, v7, v6
	v_pk_add_f32 v[12:13], v[6:7], v[8:9] neg_lo:[0,1] neg_hi:[0,1]
	v_mov_b32_e32 v11, v6
	v_pk_add_f32 v[6:7], v[12:13], v[10:11] neg_lo:[0,1] neg_hi:[0,1]
	v_cmp_nlt_f32_e64 s[0:1], 1.0, v22
	v_add_f32_e32 v7, v18, v7
	v_add_f32_e32 v6, v6, v7
	v_add_f32_e32 v7, v9, v6
	v_mul_f32_e32 v18, v17, v7
	v_mul_f32_e32 v8, v15, v18
	v_fma_f32 v10, v18, v15, -v8
	v_fmac_f32_e32 v10, v18, v16
	v_sub_f32_e32 v9, v9, v7
	v_add_f32_e32 v15, v6, v9
	v_add_f32_e32 v6, v8, v10
	v_sub_f32_e32 v9, v7, v6
	v_pk_add_f32 v[12:13], v[6:7], v[8:9] neg_lo:[0,1] neg_hi:[0,1]
	v_mov_b32_e32 v11, v6
	v_pk_add_f32 v[6:7], v[12:13], v[10:11] neg_lo:[0,1] neg_hi:[0,1]
	s_lshl_b32 s8, s18, 8
	v_add_f32_e32 v7, v15, v7
	v_add_f32_e32 v6, v6, v7
	v_add_f32_e32 v7, v19, v18
	v_add_f32_e32 v6, v9, v6
	v_sub_f32_e32 v8, v7, v19
	v_mul_f32_e32 v6, v17, v6
	v_sub_f32_e32 v8, v18, v8
	v_add_f32_e32 v8, v8, v6
	v_add_f32_e32 v10, v7, v8
	v_mul_f32_e32 v11, v10, v10
	v_fmamk_f32 v6, v11, 0x3e9b6dac, v161
	v_fmaak_f32 v83, v11, v6, 0x3f2aaada
	v_cvt_f32_i32_e32 v6, v14
	v_sub_f32_e32 v7, v10, v7
	v_sub_f32_e32 v7, v8, v7
	v_ldexp_f32 v12, v7, 1
	v_mul_f32_e32 v7, v10, v11
	v_ldexp_f32 v9, v10, 1
	v_pk_mul_f32 v[10:11], v[6:7], v[82:83]
	v_lshl_add_u64 v[4:5], v[84:85], 0, s[8:9]
	v_fma_f32 v8, v6, s15, -v10
	v_fmac_f32_e32 v8, 0xb102e308, v6
	v_pk_add_f32 v[6:7], v[10:11], v[8:9]
; #define LAS __attribute__((address_space(3)))
; DI float ret_lg2(const Params& p, int l, int dir, int h) { return log1pf(-exp2f(p.in[12][(l * 2 + dir) * 5 + h])) * 1.4426950408889634f; }
; DI void phase_ret_scan(const Params& p, int l, LAS unsigned char* lds) {
;     ...
;         const float lg = ret_lg2(p, l, dir, h), gL = exp2f(lg * 128.f);
;         float wt[4][8];
; #pragma unroll
;         for (int ks = 0; ks < 4; ++ks)
; #pragma unroll
;             for (int e = 0; e < 8; ++e) { const int pp = ks * 32 + q4 * 8 + e; wt[ks][e] = exp2f(lg * (float)(dir == 0 ? 127 - pp : pp)); }
;         const bf16_t* kt = (const bf16_t*)(ws + WS_KTR) + ((size_t)b * 640 + h * 128 + dkb * 16 + r16) * RB + q4 * 8;
;         const LAS unsigned char* vl = lds + r16 * VRS + q4 * 16;
;         bf16_t* sb = (bf16_t*)(ws + WS_S) + ((size_t)((b * 5 + h) * 2 + dir) * 18) * 16384 + (dvb * 16 + r16) * 128 + dkb * 16 + q4 * 4;
;         f32x4 st = (f32x4){0.f, 0.f, 0.f, 0.f};
;         bf16x8 ca[4];
;         { const int c0 = dir == 0 ? 0 : 1;
; #pragma unroll
;           for (int ks = 0; ks < 4; ++ks) ca[ks] = *(const bf16x8*)(kt + c0 * 128 + ks * 32); }
	global_load_dwordx4 v[0:3], v[4:5], off
	v_sub_f32_e32 v9, v7, v9
	v_sub_f32_e32 v9, v11, v9
	v_add_f32_e32 v13, v12, v9
	v_mov_b32_e32 v12, v10
	v_pk_add_f32 v[10:11], v[6:7], v[10:11] neg_lo:[0,1] neg_hi:[0,1]
	v_pk_add_f32 v[14:15], v[6:7], v[12:13]
	v_mov_b32_e32 v9, v6
	v_mov_b32_e32 v11, v15
	v_pk_add_f32 v[16:17], v[8:9], v[10:11] neg_lo:[0,1] neg_hi:[0,1]
	v_pk_add_f32 v[8:9], v[8:9], v[10:11]
	v_mov_b32_e32 v20, v7
	v_pk_add_f32 v[10:11], v[8:9], v[6:7] op_sel:[1,0] op_sel_hi:[0,1] neg_lo:[0,1] neg_hi:[0,1]
	v_pk_add_f32 v[18:19], v[14:15], v[10:11] op_sel_hi:[1,0] neg_lo:[0,1] neg_hi:[0,1]
	v_mov_b32_e32 v14, v15
	v_mov_b32_e32 v15, v9
	v_mov_b32_e32 v21, v10
	v_pk_add_f32 v[10:11], v[14:15], v[20:21] neg_lo:[0,1] neg_hi:[0,1]
	v_mov_b32_e32 v12, v13
	v_mov_b32_e32 v13, v6
	v_pk_add_f32 v[6:7], v[12:13], v[10:11] neg_lo:[0,1] neg_hi:[0,1]
	v_mov_b32_e32 v18, v16
	v_pk_add_f32 v[10:11], v[18:19], v[6:7]
	v_mov_b32_e32 v17, v9
	v_pk_add_f32 v[12:13], v[10:11], v[10:11] op_sel:[0,1] op_sel_hi:[1,0]
	v_mov_b32_e32 v81, v41
	v_pk_add_f32 v[8:9], v[8:9], v[12:13] op_sel:[1,0] op_sel_hi:[0,1]
	v_mov_b32_e32 v11, v8
	v_pk_add_f32 v[14:15], v[10:11], v[16:17] neg_lo:[0,1] neg_hi:[0,1]
	v_mov_b32_e32 v7, v12
	v_sub_f32_e32 v9, v10, v14
	v_pk_add_f32 v[6:7], v[6:7], v[14:15] neg_lo:[0,1] neg_hi:[0,1]
	v_sub_f32_e32 v9, v16, v9
	v_add_f32_e32 v6, v6, v9
	v_add_f32_e32 v6, v6, v7
	v_add_f32_e32 v6, v8, v6
	v_cndmask_b32_e64 v6, v163, v6, s[0:1]
	v_cmp_neq_f32_e64 s[0:1], 1.0, v22
	s_mov_b32 s8, 0
	s_nop 0
	v_cndmask_b32_e64 v6, v164, v6, s[0:1]
	v_cmp_lt_f32_e64 s[0:1], |v22|, s16
	s_nop 1
	v_cndmask_b32_e64 v6, v6, -v22, s[0:1]
	v_mul_f32_e32 v18, 0x3fb8aa3b, v6
	v_cndmask_b32_e32 v6, v87, v89, vcc
	v_cvt_f32_ubyte0_e32 v6, v6
	v_mul_f32_e32 v7, v18, v6
	v_cmp_gt_f32_e64 s[0:1], s13, v7
	v_mul_f32_e32 v19, 0x43000000, v18
	v_mov_b32_e32 v22, 0
	v_cndmask_b32_e64 v7, 0, v162, s[0:1]
	v_fmac_f32_e32 v7, v18, v6
	v_exp_f32_e32 v6, v7
	v_cndmask_b32_e64 v7, 0, v165, s[0:1]
	v_mov_b32_e32 v23, v22
	v_mov_b32_e32 v24, v22
	v_ldexp_f32 v26, v6, v7
	v_cndmask_b32_e32 v6, v90, v91, vcc
	v_cvt_f32_ubyte0_e32 v6, v6
	v_mul_f32_e32 v7, v18, v6
	v_cmp_gt_f32_e64 s[0:1], s13, v7
	v_mov_b32_e32 v25, v22
	s_nop 0
	v_cndmask_b32_e64 v7, 0, v162, s[0:1]
	v_fmac_f32_e32 v7, v18, v6
	v_exp_f32_e32 v6, v7
	v_cndmask_b32_e32 v7, v92, v93, vcc
	v_cvt_f32_ubyte0_e32 v7, v7
	v_mul_f32_e32 v8, v18, v7
	v_cmp_gt_f32_e64 s[2:3], s13, v8
	s_nop 1
	v_cndmask_b32_e64 v8, 0, v162, s[2:3]
	v_fmac_f32_e32 v8, v18, v7
	v_exp_f32_e32 v7, v8
	v_cndmask_b32_e64 v8, 0, v165, s[0:1]
	v_ldexp_f32 v27, v6, v8
	v_cndmask_b32_e64 v6, 0, v165, s[2:3]
	v_ldexp_f32 v28, v7, v6
	v_cndmask_b32_e32 v6, v94, v95, vcc
	v_cvt_f32_ubyte0_e32 v6, v6
	v_mul_f32_e32 v7, v18, v6
	v_cmp_gt_f32_e64 s[0:1], s13, v7
	s_nop 1
	v_cndmask_b32_e64 v7, 0, v162, s[0:1]
	v_fmac_f32_e32 v7, v18, v6
	v_exp_f32_e32 v6, v7
	v_cndmask_b32_e32 v7, v96, v97, vcc
	v_cvt_f32_ubyte0_e32 v7, v7
	v_mul_f32_e32 v8, v18, v7
	v_cmp_gt_f32_e64 s[2:3], s13, v8
	s_nop 1
	v_cndmask_b32_e64 v8, 0, v162, s[2:3]
	v_fmac_f32_e32 v8, v18, v7
	v_exp_f32_e32 v7, v8
	v_cndmask_b32_e64 v8, 0, v165, s[0:1]
	v_ldexp_f32 v29, v6, v8
	v_cndmask_b32_e64 v6, 0, v165, s[2:3]
	v_ldexp_f32 v30, v7, v6
	v_cndmask_b32_e32 v6, v98, v99, vcc
	v_cvt_f32_ubyte0_e32 v6, v6
	v_mul_f32_e32 v7, v18, v6
	v_cmp_gt_f32_e64 s[0:1], s13, v7
	s_nop 1
	v_cndmask_b32_e64 v7, 0, v162, s[0:1]
	v_fmac_f32_e32 v7, v18, v6
	v_exp_f32_e32 v6, v7
	v_cndmask_b32_e32 v7, v100, v101, vcc
	v_cvt_f32_ubyte0_e32 v7, v7
	v_mul_f32_e32 v8, v18, v7
	v_cmp_gt_f32_e64 s[2:3], s13, v8
	s_nop 1
	v_cndmask_b32_e64 v8, 0, v162, s[2:3]
	v_fmac_f32_e32 v8, v18, v7
	v_exp_f32_e32 v7, v8
	v_cndmask_b32_e64 v8, 0, v165, s[0:1]
	v_ldexp_f32 v31, v6, v8
	v_cndmask_b32_e64 v6, 0, v165, s[2:3]
	v_ldexp_f32 v32, v7, v6
	v_cndmask_b32_e32 v6, v102, v103, vcc
	v_cvt_f32_ubyte0_e32 v6, v6
	v_mul_f32_e32 v7, v18, v6
	v_cmp_gt_f32_e64 s[0:1], s13, v7
	s_nop 1
	v_cndmask_b32_e64 v7, 0, v162, s[0:1]
	v_fmac_f32_e32 v7, v18, v6
	v_exp_f32_e32 v6, v7
	v_cndmask_b32_e32 v7, v104, v105, vcc
	v_cvt_f32_ubyte0_e32 v7, v7
	v_mul_f32_e32 v8, v18, v7
	v_cmp_gt_f32_e64 s[2:3], s13, v8
	s_nop 1
	v_cndmask_b32_e64 v8, 0, v162, s[2:3]
	v_fmac_f32_e32 v8, v18, v7
	v_exp_f32_e32 v7, v8
	v_cndmask_b32_e64 v8, 0, v165, s[0:1]
	v_ldexp_f32 v33, v6, v8
	v_cndmask_b32_e64 v6, 0, v165, s[2:3]
	v_ldexp_f32 v34, v7, v6
	v_cndmask_b32_e32 v6, v106, v107, vcc
	v_cvt_f32_ubyte0_e32 v6, v6
	v_mul_f32_e32 v7, v18, v6
	v_cmp_gt_f32_e64 s[0:1], s13, v7
	s_nop 1
	v_cndmask_b32_e64 v7, 0, v162, s[0:1]
	v_fmac_f32_e32 v7, v18, v6
	v_exp_f32_e32 v6, v7
	v_cndmask_b32_e32 v7, v108, v109, vcc
	v_cvt_f32_ubyte0_e32 v7, v7
	v_mul_f32_e32 v8, v18, v7
	v_cmp_gt_f32_e64 s[2:3], s13, v8
	s_nop 1
	v_cndmask_b32_e64 v8, 0, v162, s[2:3]
	v_fmac_f32_e32 v8, v18, v7
	v_exp_f32_e32 v7, v8
	v_cndmask_b32_e64 v8, 0, v165, s[0:1]
	v_ldexp_f32 v35, v6, v8
	v_cndmask_b32_e64 v6, 0, v165, s[2:3]
	v_ldexp_f32 v83, v7, v6
	v_cndmask_b32_e32 v6, v110, v111, vcc
	v_cvt_f32_ubyte0_e32 v6, v6
	v_mul_f32_e32 v7, v18, v6
	v_cmp_gt_f32_e64 s[0:1], s13, v7
	s_nop 1
	v_cndmask_b32_e64 v7, 0, v162, s[0:1]
	v_fmac_f32_e32 v7, v18, v6
	v_exp_f32_e32 v6, v7
	v_cndmask_b32_e32 v7, v112, v113, vcc
	v_cvt_f32_ubyte0_e32 v7, v7
	v_mul_f32_e32 v8, v18, v7
	v_cmp_gt_f32_e64 s[2:3], s13, v8
	s_nop 1
	v_cndmask_b32_e64 v8, 0, v162, s[2:3]
	v_fmac_f32_e32 v8, v18, v7
	v_exp_f32_e32 v7, v8
	v_cndmask_b32_e64 v8, 0, v165, s[0:1]
	v_ldexp_f32 v166, v6, v8
	v_cndmask_b32_e64 v6, 0, v165, s[2:3]
	v_ldexp_f32 v167, v7, v6
	v_cndmask_b32_e32 v6, v114, v115, vcc
	v_cvt_f32_ubyte0_e32 v6, v6
; #define LAS __attribute__((address_space(3)))
; DI void phase_ret_scan(const Params& p, int l, LAS unsigned char* lds) {
;     ...
;         for (int ks = 0; ks < 4; ++ks)
; #pragma unroll
;             for (int e = 0; e < 8; ++e) { const int pp = ks * 32 + q4 * 8 + e; wt[ks][e] = exp2f(lg * (float)(dir == 0 ? 127 - pp : pp)); }
;         const bf16_t* kt = (const bf16_t*)(ws + WS_KTR) + ((size_t)b * 640 + h * 128 + dkb * 16 + r16) * RB + q4 * 8;
;         const LAS unsigned char* vl = lds + r16 * VRS + q4 * 16;
;         bf16_t* sb = (bf16_t*)(ws + WS_S) + ((size_t)((b * 5 + h) * 2 + dir) * 18) * 16384 + (dvb * 16 + r16) * 128 + dkb * 16 + q4 * 4;
;         f32x4 st = (f32x4){0.f, 0.f, 0.f, 0.f};
;         bf16x8 ca[4];
;         { const int c0 = dir == 0 ? 0 : 1;
; #pragma unroll
;           for (int ks = 0; ks < 4; ++ks) ca[ks] = *(const bf16x8*)(kt + c0 * 128 + ks * 32); }
;         __syncthreads();
; #pragma unroll 2
;         for (int step = 0; step < 18; ++step) {
;             const int c = dir == 0 ? step : (step < 2 ? 1 - step : 19 - step);
;             const int sn = step < 17 ? step + 1 : 17;
;             const int cn = dir == 0 ? sn : (sn < 2 ? 1 - sn : 19 - sn);
;             bf16x8 na_[4];
; #pragma unroll
;             for (int ks = 0; ks < 4; ++ks) na_[ks] = *(const bf16x8*)(kt + cn * 128 + ks * 32);
	v_mul_f32_e32 v7, v18, v6
	v_cmp_gt_f32_e64 s[0:1], s13, v7
	s_nop 1
	v_cndmask_b32_e64 v7, 0, v162, s[0:1]
	v_fmac_f32_e32 v7, v18, v6
	v_exp_f32_e32 v6, v7
	v_cndmask_b32_e32 v7, v116, v117, vcc
	v_cvt_f32_ubyte0_e32 v7, v7
	v_mul_f32_e32 v8, v18, v7
	v_cmp_gt_f32_e64 s[2:3], s13, v8
	s_nop 1
	v_cndmask_b32_e64 v8, 0, v162, s[2:3]
	v_fmac_f32_e32 v8, v18, v7
	v_exp_f32_e32 v7, v8
	v_cndmask_b32_e64 v8, 0, v165, s[0:1]
	v_ldexp_f32 v168, v6, v8
	v_cndmask_b32_e64 v6, 0, v165, s[2:3]
	v_ldexp_f32 v169, v7, v6
	v_cndmask_b32_e32 v6, v118, v119, vcc
	v_cvt_f32_ubyte0_e32 v6, v6
	v_mul_f32_e32 v7, v18, v6
	v_cmp_gt_f32_e64 s[0:1], s13, v7
	s_nop 1
	v_cndmask_b32_e64 v7, 0, v162, s[0:1]
	v_fmac_f32_e32 v7, v18, v6
	v_exp_f32_e32 v6, v7
	v_cndmask_b32_e32 v7, v120, v121, vcc
	v_cvt_f32_ubyte0_e32 v7, v7
	v_mul_f32_e32 v8, v18, v7
	v_cmp_gt_f32_e64 s[2:3], s13, v8
	s_nop 1
	v_cndmask_b32_e64 v8, 0, v162, s[2:3]
	v_fmac_f32_e32 v8, v18, v7
	v_exp_f32_e32 v7, v8
	v_cndmask_b32_e64 v8, 0, v165, s[0:1]
	v_ldexp_f32 v170, v6, v8
	v_cndmask_b32_e64 v6, 0, v165, s[2:3]
	v_ldexp_f32 v171, v7, v6
	v_cndmask_b32_e32 v6, v122, v123, vcc
	v_cvt_f32_ubyte0_e32 v6, v6
	v_mul_f32_e32 v7, v18, v6
	v_cmp_gt_f32_e64 s[0:1], s13, v7
	s_nop 1
	v_cndmask_b32_e64 v7, 0, v162, s[0:1]
	v_fmac_f32_e32 v7, v18, v6
	v_exp_f32_e32 v6, v7
	v_cndmask_b32_e32 v7, v124, v125, vcc
	v_cvt_f32_ubyte0_e32 v7, v7
	v_mul_f32_e32 v8, v18, v7
	v_cmp_gt_f32_e64 s[2:3], s13, v8
	s_nop 1
	v_cndmask_b32_e64 v8, 0, v162, s[2:3]
	v_fmac_f32_e32 v8, v18, v7
	v_exp_f32_e32 v7, v8
	v_cndmask_b32_e64 v8, 0, v165, s[0:1]
	v_ldexp_f32 v172, v6, v8
	v_cndmask_b32_e64 v6, 0, v165, s[2:3]
	v_ldexp_f32 v173, v7, v6
	v_cndmask_b32_e32 v6, v126, v127, vcc
	v_cvt_f32_ubyte0_e32 v6, v6
	v_mul_f32_e32 v7, v18, v6
	v_cmp_gt_f32_e64 s[0:1], s13, v7
	s_nop 1
	v_cndmask_b32_e64 v7, 0, v162, s[0:1]
	v_fmac_f32_e32 v7, v18, v6
	v_exp_f32_e32 v6, v7
	v_cndmask_b32_e32 v7, v128, v129, vcc
	v_cvt_f32_ubyte0_e32 v7, v7
	v_mul_f32_e32 v8, v18, v7
	v_cmp_gt_f32_e64 s[2:3], s13, v8
	s_nop 1
	v_cndmask_b32_e64 v8, 0, v162, s[2:3]
	v_fmac_f32_e32 v8, v18, v7
	v_exp_f32_e32 v7, v8
	v_cndmask_b32_e64 v8, 0, v165, s[0:1]
	v_ldexp_f32 v174, v6, v8
	v_cndmask_b32_e64 v6, 0, v165, s[2:3]
	v_ldexp_f32 v175, v7, v6
	v_cndmask_b32_e32 v6, v130, v131, vcc
	v_cvt_f32_ubyte0_e32 v6, v6
	v_mul_f32_e32 v7, v18, v6
	v_cmp_gt_f32_e64 s[0:1], s13, v7
	s_nop 1
	v_cndmask_b32_e64 v7, 0, v162, s[0:1]
	v_fmac_f32_e32 v7, v18, v6
	v_exp_f32_e32 v6, v7
	v_cndmask_b32_e32 v7, v132, v133, vcc
	v_cvt_f32_ubyte0_e32 v7, v7
	v_mul_f32_e32 v8, v18, v7
	v_cmp_gt_f32_e64 s[2:3], s13, v8
	s_nop 1
	v_cndmask_b32_e64 v8, 0, v162, s[2:3]
	v_fmac_f32_e32 v8, v18, v7
	v_exp_f32_e32 v7, v8
	v_cndmask_b32_e64 v8, 0, v165, s[0:1]
	v_ldexp_f32 v176, v6, v8
	v_cndmask_b32_e64 v6, 0, v165, s[2:3]
	v_ldexp_f32 v177, v7, v6
	v_cndmask_b32_e32 v6, v134, v135, vcc
	v_cvt_f32_ubyte0_e32 v6, v6
	v_mul_f32_e32 v7, v18, v6
	v_cmp_gt_f32_e64 s[0:1], s13, v7
	s_nop 1
	v_cndmask_b32_e64 v7, 0, v162, s[0:1]
	v_fmac_f32_e32 v7, v18, v6
	v_exp_f32_e32 v6, v7
	v_cndmask_b32_e32 v7, v136, v137, vcc
	v_cvt_f32_ubyte0_e32 v7, v7
	v_mul_f32_e32 v8, v18, v7
	v_cmp_gt_f32_e64 s[2:3], s13, v8
	s_nop 1
	v_cndmask_b32_e64 v8, 0, v162, s[2:3]
	v_fmac_f32_e32 v8, v18, v7
	v_exp_f32_e32 v7, v8
	v_cndmask_b32_e64 v8, 0, v165, s[0:1]
	v_ldexp_f32 v178, v6, v8
	v_cndmask_b32_e64 v6, 0, v165, s[2:3]
	v_ldexp_f32 v179, v7, v6
	v_cndmask_b32_e32 v6, v138, v139, vcc
	v_cvt_f32_ubyte0_e32 v6, v6
	v_mul_f32_e32 v7, v18, v6
	v_cmp_gt_f32_e64 s[0:1], s13, v7
	s_nop 1
	v_cndmask_b32_e64 v7, 0, v162, s[0:1]
	v_fmac_f32_e32 v7, v18, v6
	v_exp_f32_e32 v16, v7
	global_load_dwordx4 v[12:15], v[4:5], off offset:64
	global_load_dwordx4 v[8:11], v[4:5], off offset:128
	s_nop 0
	global_load_dwordx4 v[4:7], v[4:5], off offset:192
	v_lshlrev_b32_e32 v254, 4, v202
	v_add_u32_e32 v254, 0x14000, v254
	ds_write_b128 v254, v[92:95]
	ds_write_b128 v254, v[96:99] offset:8192
	ds_write_b128 v254, v[100:103] offset:16384
	ds_write_b128 v254, v[104:107] offset:24576
	s_waitcnt lgkmcnt(0)
	s_and_b64 s[100:101], vcc, exec
	s_cselect_b32 s98, 1, 0
	s_lshl_b32 s98, s98, 8
	s_mov_b32 s99, 0
	v_lshl_add_u64 v[250:251], s[98:99], 0, v[84:85]
	global_load_dwordx4 v[92:95], v[250:251], off
	global_load_dwordx4 v[96:99], v[250:251], off offset:64
	global_load_dwordx4 v[100:103], v[250:251], off offset:128
	global_load_dwordx4 v[104:107], v[250:251], off offset:192
	s_and_b64 s[100:101], vcc, exec
	s_cselect_b32 s98, 2, 17
	s_lshl_b32 s98, s98, 8
	v_lshl_add_u64 v[250:251], s[98:99], 0, v[84:85]
	global_load_dwordx4 v[234:237], v[250:251], off
	global_load_dwordx4 v[238:241], v[250:251], off offset:64
	global_load_dwordx4 v[242:245], v[250:251], off offset:128
	global_load_dwordx4 v[246:249], v[250:251], off offset:192
	v_cndmask_b32_e64 v17, 0, v165, s[0:1]
	s_waitcnt lgkmcnt(0)
	v_ldexp_f32 v180, v16, v17
	v_cndmask_b32_e32 v16, v140, v141, vcc
	v_cvt_f32_ubyte0_e32 v16, v16
	v_mul_f32_e32 v17, v18, v16
	v_cmp_gt_f32_e64 s[0:1], s13, v17
	s_barrier
; #define LAS __attribute__((address_space(3)))
; DI void st_bf16x4(bf16_t* p, f32x4 v) { u32x2 w; w.x = cvt_pk_bf16(v[0], v[1]); w.y = cvt_pk_bf16(v[2], v[3]); *(u32x2*)p = w; }
; #define MFMA16(a, b, c) __builtin_amdgcn_mfma_f32_16x16x32_bf16((a), (b), (c), 0, 0, 0)
; DI void phase_ret_scan(const Params& p, int l, LAS unsigned char* lds) {
;     ...
;         for (int step = 0; step < 18; ++step) {
;             const int c = dir == 0 ? step : (step < 2 ? 1 - step : 19 - step);
;             const int sn = step < 17 ? step + 1 : 17;
;             const int cn = dir == 0 ? sn : (sn < 2 ? 1 - sn : 19 - sn);
;             bf16x8 na_[4];
; #pragma unroll
;             for (int ks = 0; ks < 4; ++ks) na_[ks] = *(const bf16x8*)(kt + cn * 128 + ks * 32);
;             st_bf16x4(sb + (size_t)c * 16384, st);
;             f32x4 u = (f32x4){0.f, 0.f, 0.f, 0.f};
; #pragma unroll
;             for (int ks = 0; ks < 4; ++ks) u = MFMA16(scale_bf16x8(ca[ks], wt[ks]), *(const LAS bf16x8*)(vl + (c * 128 + ks * 32) * 2), u);
;             st = st * gL + u;
; #pragma unroll
;             for (int ks = 0; ks < 4; ++ks) ca[ks] = na_[ks];
	s_nop 0
	v_cndmask_b32_e64 v17, 0, v162, s[0:1]
	v_fmac_f32_e32 v17, v18, v16
	v_exp_f32_e32 v16, v17
	v_cndmask_b32_e32 v17, v142, v143, vcc
	v_cvt_f32_ubyte0_e32 v17, v17
	v_mul_f32_e32 v20, v18, v17
	v_cmp_gt_f32_e64 s[2:3], s13, v20
	s_nop 1
	v_cndmask_b32_e64 v20, 0, v162, s[2:3]
	v_fmac_f32_e32 v20, v18, v17
	v_exp_f32_e32 v17, v20
	v_cndmask_b32_e64 v20, 0, v165, s[0:1]
	v_ldexp_f32 v181, v16, v20
	v_cndmask_b32_e64 v16, 0, v165, s[2:3]
	v_ldexp_f32 v182, v17, v16
	v_cndmask_b32_e32 v16, v144, v145, vcc
	v_cvt_f32_ubyte0_e32 v16, v16
	v_mul_f32_e32 v17, v18, v16
	v_cmp_gt_f32_e64 s[0:1], s13, v17
	s_nop 1
	v_cndmask_b32_e64 v17, 0, v162, s[0:1]
	v_fmac_f32_e32 v17, v18, v16
	v_exp_f32_e32 v16, v17
	v_cndmask_b32_e32 v17, v146, v147, vcc
	v_cvt_f32_ubyte0_e32 v17, v17
	v_mul_f32_e32 v20, v18, v17
	v_cmp_gt_f32_e64 s[2:3], s13, v20
	s_nop 1
	v_cndmask_b32_e64 v20, 0, v162, s[2:3]
	v_fmac_f32_e32 v20, v18, v17
	v_exp_f32_e32 v17, v20
	v_cndmask_b32_e64 v20, 0, v165, s[0:1]
	v_ldexp_f32 v183, v16, v20
	v_cndmask_b32_e64 v16, 0, v165, s[2:3]
	v_ldexp_f32 v184, v17, v16
	v_cndmask_b32_e32 v16, v148, v149, vcc
	v_cvt_f32_ubyte0_e32 v16, v16
	v_mul_f32_e32 v17, v18, v16
	v_cmp_gt_f32_e64 s[0:1], s13, v17
	s_nop 1
	v_cndmask_b32_e64 v17, 0, v162, s[0:1]
	v_fmac_f32_e32 v17, v18, v16
	v_exp_f32_e32 v16, v17
	v_cndmask_b32_e32 v17, v150, v151, vcc
	v_cvt_f32_ubyte0_e32 v17, v17
	v_mul_f32_e32 v20, v18, v17
	v_cmp_gt_f32_e64 s[2:3], s13, v20
	s_nop 1
	v_cndmask_b32_e64 v20, 0, v162, s[2:3]
	v_fmac_f32_e32 v20, v18, v17
	v_exp_f32_e32 v17, v20
	v_cndmask_b32_e64 v20, 0, v165, s[0:1]
	v_cmp_gt_f32_e64 s[0:1], s13, v19
	v_ldexp_f32 v185, v16, v20
	v_cndmask_b32_e64 v16, 0, v165, s[2:3]
	v_cndmask_b32_e64 v19, 0, v162, s[0:1]
	v_fmac_f32_e32 v19, 0x43000000, v18
	v_exp_f32_e32 v18, v19
	v_ldexp_f32 v186, v17, v16
	v_or_b32_e32 v16, s17, v86
	v_lshlrev_b32_e32 v40, 8, v16
	s_and_b64 s[0:1], s[0:1], exec
	v_lshl_add_u64 v[16:17], s[10:11], 0, v[40:41]
	s_cselect_b32 s0, 0xffffffc0, 0
	v_lshl_add_u64 v[16:17], v[36:37], 1, v[16:17]
	v_ldexp_f32 v18, v18, s0
	v_lshl_add_u64 v[16:17], v[16:17], 0, v[80:81]
	v_mov_b32_e32 v20, v18
	v_mov_b32_e32 v21, v18
	s_mov_b32 s0, 0
	s_waitcnt vmcnt(8)
.LBB0_2531:
	s_cmp_eq_u32 s8, 0
	s_cselect_b32 s1, 1, 19
	s_add_i32 s1, s1, s8
	s_or_b32 s10, s0, 1
	s_add_i32 s11, s1, -1
	s_and_b64 s[2:3], vcc, exec
	s_cselect_b32 s2, s10, s11
	s_lshl_b32 s10, s2, 7
	v_lshlrev_b32_e32 v40, 16, v0
	v_and_b32_e32 v0, 0xffff0000, v0
	v_lshlrev_b32_e32 v81, 16, v1
	v_and_b32_e32 v1, 0xffff0000, v1
	s_ashr_i32 s11, s10, 31
	v_lshlrev_b32_e32 v188, 16, v3
	v_lshlrev_b32_e32 v189, 16, v12
	v_lshlrev_b32_e32 v190, 16, v13
	v_lshlrev_b32_e32 v191, 16, v14
	v_lshlrev_b32_e32 v192, 16, v15
	v_lshlrev_b32_e32 v193, 16, v8
	v_lshlrev_b32_e32 v194, 16, v9
	v_lshlrev_b32_e32 v195, 16, v10
	v_lshlrev_b32_e32 v196, 16, v11
	v_lshlrev_b32_e32 v197, 16, v4
	v_lshlrev_b32_e32 v198, 16, v5
	v_lshlrev_b32_e32 v199, 16, v6
	v_mul_f32_e32 v201, v27, v0
	v_mul_f32_e32 v208, v29, v1
	v_lshl_add_u64 v[0:1], s[10:11], 1, v[84:85]
	v_mul_f32_e32 v210, v32, v188
	v_mul_f32_e32 v212, v34, v189
	v_mul_f32_e32 v213, v83, v190
	v_mul_f32_e32 v214, v167, v191
	v_mul_f32_e32 v215, v169, v192
	v_mul_f32_e32 v216, v171, v193
	v_mul_f32_e32 v218, v173, v194
	v_mul_f32_e32 v220, v175, v195
	v_mul_f32_e32 v222, v177, v196
	v_mul_f32_e32 v224, v179, v197
	v_mul_f32_e32 v226, v181, v198
	v_mul_f32_e32 v228, v183, v199
	s_and_b64 s[10:11], vcc, exec
	s_cselect_b32 s10, s0, s1
	s_ashr_i32 s11, s10, 31
	v_lshlrev_b32_e32 v187, 16, v2
	v_and_b32_e32 v2, 0xffff0000, v2
	v_and_b32_e32 v3, 0xffff0000, v3
	s_cmp_eq_u32 s0, 0
	s_cbranch_scc1 sc1_a
	s_waitcnt vmcnt(6)
	s_branch sc1_b
sc1_a:
	s_waitcnt vmcnt(4)
sc1_b:
	v_mov_b32_e32 v188, v92
	v_mov_b32_e32 v189, v93
	v_mov_b32_e32 v190, v94
	v_mov_b32_e32 v191, v95
	v_mov_b32_e32 v192, v96
	v_mov_b32_e32 v193, v97
	v_mov_b32_e32 v194, v98
	v_mov_b32_e32 v195, v99
	v_mov_b32_e32 v196, v100
	v_mov_b32_e32 v197, v101
	v_mov_b32_e32 v198, v102
	v_mov_b32_e32 v199, v103
	v_mov_b32_e32 v204, v104
	v_mov_b32_e32 v205, v105
	v_mov_b32_e32 v206, v106
	v_mov_b32_e32 v207, v107
	s_add_u32 s98, s0, 3
	s_min_u32 s98, s98, 17
	s_sub_u32 s99, 19, s98
	s_and_b64 s[100:101], vcc, exec
	s_cselect_b32 s98, s98, s99
	s_lshl_b32 s98, s98, 8
	s_mov_b32 s99, 0
	v_lshl_add_u64 v[250:251], s[98:99], 0, v[84:85]
	global_load_dwordx4 v[92:95], v[250:251], off
	global_load_dwordx4 v[96:99], v[250:251], off offset:64
	global_load_dwordx4 v[100:103], v[250:251], off offset:128
	global_load_dwordx4 v[104:107], v[250:251], off offset:192
	v_lshl_add_u32 v232, s10, 8, v88
	s_lshl_b64 s[10:11], s[10:11], 15
	v_and_b32_e32 v4, 0xffff0000, v4
	v_and_b32_e32 v5, 0xffff0000, v5
	v_and_b32_e32 v6, 0xffff0000, v6
	v_lshlrev_b32_e32 v200, 16, v7
	v_and_b32_e32 v7, 0xffff0000, v7
	v_mul_f32_e32 v209, v31, v2
	v_mul_f32_e32 v211, v33, v3
	v_cvt_pk_bf16_f32 v0, v22, v23
	v_cvt_pk_bf16_f32 v1, v24, v25
	v_lshl_add_u64 v[2:3], v[16:17], 0, s[10:11]
	v_mul_f32_e32 v40, v26, v40
	v_mul_f32_e32 v81, v28, v81
	v_mul_f32_e32 v187, v30, v187
	v_mul_f32_e32 v225, v180, v4
	v_mul_f32_e32 v227, v182, v5
	v_mul_f32_e32 v229, v184, v6
	v_mul_f32_e32 v230, v186, v7
	global_store_dwordx2 v[2:3], v[0:1], off
	v_cvt_pk_bf16_f32 v0, v40, v201
	v_cvt_pk_bf16_f32 v1, v81, v208
	v_cvt_pk_bf16_f32 v2, v187, v209
	v_cvt_pk_bf16_f32 v3, v210, v211
	ds_read_b128 v[4:7], v232
	v_and_b32_e32 v12, 0xffff0000, v12
	v_and_b32_e32 v13, 0xffff0000, v13
	v_and_b32_e32 v14, 0xffff0000, v14
	v_and_b32_e32 v15, 0xffff0000, v15
	s_add_i32 s1, s0, 2
	v_and_b32_e32 v8, 0xffff0000, v8
	v_and_b32_e32 v9, 0xffff0000, v9
	v_and_b32_e32 v10, 0xffff0000, v10
	v_and_b32_e32 v11, 0xffff0000, v11
	v_mul_f32_e32 v12, v35, v12
	v_mul_f32_e32 v13, v166, v13
	v_mul_f32_e32 v14, v168, v14
	v_mul_f32_e32 v15, v170, v15
	s_cmp_lg_u32 s0, 16
	v_mul_f32_e32 v217, v172, v8
	v_mul_f32_e32 v219, v174, v9
	v_mul_f32_e32 v221, v176, v10
	v_mul_f32_e32 v223, v178, v11
	v_cvt_pk_bf16_f32 v8, v212, v12
	v_cvt_pk_bf16_f32 v9, v213, v13
	v_cvt_pk_bf16_f32 v10, v214, v14
	v_cvt_pk_bf16_f32 v11, v215, v15
	ds_read_b128 v[12:15], v232 offset:64
	s_cselect_b32 s0, s1, 17
	s_cmp_gt_u32 s0, 1
	s_waitcnt lgkmcnt(1)
; #define LAS __attribute__((address_space(3)))
; DI void st_bf16x4(bf16_t* p, f32x4 v) { u32x2 w; w.x = cvt_pk_bf16(v[0], v[1]); w.y = cvt_pk_bf16(v[2], v[3]); *(u32x2*)p = w; }
; #define MFMA16(a, b, c) __builtin_amdgcn_mfma_f32_16x16x32_bf16((a), (b), (c), 0, 0, 0)
; DI void phase_ret_scan(const Params& p, int l, LAS unsigned char* lds) {
;     ...
;         for (int step = 0; step < 18; ++step) {
;             const int c = dir == 0 ? step : (step < 2 ? 1 - step : 19 - step);
;             const int sn = step < 17 ? step + 1 : 17;
;             const int cn = dir == 0 ? sn : (sn < 2 ? 1 - sn : 19 - sn);
;             bf16x8 na_[4];
; #pragma unroll
;             for (int ks = 0; ks < 4; ++ks) na_[ks] = *(const bf16x8*)(kt + cn * 128 + ks * 32);
;             st_bf16x4(sb + (size_t)c * 16384, st);
;             f32x4 u = (f32x4){0.f, 0.f, 0.f, 0.f};
; #pragma unroll
;             for (int ks = 0; ks < 4; ++ks) u = MFMA16(scale_bf16x8(ca[ks], wt[ks]), *(const LAS bf16x8*)(vl + (c * 128 + ks * 32) * 2), u);
;             st = st * gL + u;
; #pragma unroll
;             for (int ks = 0; ks < 4; ++ks) ca[ks] = na_[ks];
	v_mfma_f32_16x16x32_bf16 v[0:3], v[0:3], v[4:7], 0
	s_cselect_b32 s3, 19, 1
	s_sub_i32 s3, s3, s0
	v_cvt_pk_bf16_f32 v208, v216, v217
	v_cvt_pk_bf16_f32 v209, v218, v219
	v_cvt_pk_bf16_f32 v210, v220, v221
	v_cvt_pk_bf16_f32 v211, v222, v223
	ds_read_b128 v[212:215], v232 offset:128
	s_and_b64 s[10:11], vcc, exec
	s_cselect_b32 s0, s0, s3
	s_waitcnt lgkmcnt(1)
	v_mfma_f32_16x16x32_bf16 v[4:7], v[8:11], v[12:15], v[0:3]
	s_lshl_b32 s10, s0, 7
	s_ashr_i32 s11, s10, 31
	v_cvt_pk_bf16_f32 v216, v224, v225
	v_lshl_add_u64 v[224:225], s[10:11], 1, v[84:85]
	v_mul_f32_e32 v200, v185, v200
	v_cvt_pk_bf16_f32 v217, v226, v227
	v_cvt_pk_bf16_f32 v218, v228, v229
	v_cvt_pk_bf16_f32 v219, v200, v230
	ds_read_b128 v[220:223], v232 offset:192
	s_waitcnt lgkmcnt(1)
	v_mfma_f32_16x16x32_bf16 v[208:211], v[208:211], v[212:215], v[4:7]
	s_nop 0
	s_nop 3
	s_cmp_eq_u32 s1, 2
	s_cbranch_scc1 sc1_c
	s_waitcnt vmcnt(6)
	s_branch sc1_d
sc1_c:
	s_waitcnt vmcnt(5)
sc1_d:
	v_mov_b32_e32 v0, v234
	v_mov_b32_e32 v1, v235
	v_mov_b32_e32 v2, v236
	v_mov_b32_e32 v3, v237
	v_mov_b32_e32 v12, v238
	v_mov_b32_e32 v13, v239
	v_mov_b32_e32 v14, v240
	v_mov_b32_e32 v15, v241
	v_mov_b32_e32 v8, v242
	v_mov_b32_e32 v9, v243
	v_mov_b32_e32 v10, v244
	v_mov_b32_e32 v11, v245
	v_mov_b32_e32 v4, v246
	v_mov_b32_e32 v5, v247
	v_mov_b32_e32 v6, v248
	v_mov_b32_e32 v7, v249
	s_add_u32 s98, s1, 2
	s_min_u32 s98, s98, 17
	s_sub_u32 s99, 19, s98
	s_and_b64 s[100:101], vcc, exec
	s_cselect_b32 s98, s98, s99
	s_lshl_b32 s98, s98, 8
	s_mov_b32 s99, 0
	v_lshl_add_u64 v[250:251], s[98:99], 0, v[84:85]
	global_load_dwordx4 v[234:237], v[250:251], off
	global_load_dwordx4 v[238:241], v[250:251], off offset:64
	global_load_dwordx4 v[242:245], v[250:251], off offset:128
	global_load_dwordx4 v[246:249], v[250:251], off offset:192
	s_ashr_i32 s3, s2, 31
	v_mov_b32_e32 v19, v18
	s_waitcnt lgkmcnt(0)
	v_mfma_f32_16x16x32_bf16 v[208:211], v[216:219], v[220:223], v[208:211]
	v_lshl_add_u32 v231, s2, 8, v88
	s_lshl_b64 s[2:3], s[2:3], 15
	v_lshl_add_u64 v[200:201], v[16:17], 0, s[2:3]
	v_lshlrev_b32_e32 v40, 16, v190
	v_and_b32_e32 v81, 0xffff0000, v190
	s_nop 1
	v_pk_fma_f32 v[212:213], v[18:19], v[24:25], v[210:211]
	v_pk_fma_f32 v[214:215], v[20:21], v[22:23], v[208:209]
	v_lshlrev_b32_e32 v24, 16, v189
	v_cvt_pk_bf16_f32 v22, v214, v215
	v_cvt_pk_bf16_f32 v23, v212, v213
	global_store_dwordx2 v[200:201], v[22:23], off
	v_lshlrev_b32_e32 v22, 16, v188
	v_and_b32_e32 v23, 0xffff0000, v188
	v_and_b32_e32 v25, 0xffff0000, v189
	v_and_b32_e32 v188, 0xffff0000, v191
	v_lshlrev_b32_e32 v187, 16, v191
	v_lshlrev_b32_e32 v189, 16, v192
	v_and_b32_e32 v190, 0xffff0000, v192
	v_lshlrev_b32_e32 v191, 16, v193
	v_mul_f32_e32 v22, v26, v22
	v_mul_f32_e32 v23, v27, v23
	v_mul_f32_e32 v24, v28, v24
	v_mul_f32_e32 v25, v29, v25
	v_mul_f32_e32 v188, v33, v188
	v_mul_f32_e32 v40, v30, v40
	v_mul_f32_e32 v81, v31, v81
	v_mul_f32_e32 v187, v32, v187
	v_mul_f32_e32 v219, v34, v189
	v_mul_f32_e32 v220, v35, v190
	v_mul_f32_e32 v221, v83, v191
	v_cvt_pk_bf16_f32 v22, v22, v23
	v_cvt_pk_bf16_f32 v23, v24, v25
	v_cvt_pk_bf16_f32 v24, v40, v81
	v_cvt_pk_bf16_f32 v25, v187, v188
	ds_read_b128 v[188:191], v231
	v_and_b32_e32 v192, 0xffff0000, v193
	v_lshlrev_b32_e32 v193, 16, v194
	v_and_b32_e32 v194, 0xffff0000, v194
	v_lshlrev_b32_e32 v200, 16, v195
	v_and_b32_e32 v195, 0xffff0000, v195
	v_lshlrev_b32_e32 v201, 16, v196
	v_and_b32_e32 v196, 0xffff0000, v196
	v_lshlrev_b32_e32 v208, 16, v197
	v_and_b32_e32 v197, 0xffff0000, v197
	v_lshlrev_b32_e32 v209, 16, v198
	v_and_b32_e32 v198, 0xffff0000, v198
	v_lshlrev_b32_e32 v210, 16, v199
	v_and_b32_e32 v199, 0xffff0000, v199
	v_mul_f32_e32 v194, v168, v194
	v_mul_f32_e32 v195, v170, v195
	v_mul_f32_e32 v222, v166, v192
	v_mul_f32_e32 v223, v167, v193
	v_mul_f32_e32 v200, v169, v200
	v_mul_f32_e32 v224, v172, v196
	v_mul_f32_e32 v225, v174, v197
	v_mul_f32_e32 v226, v176, v198
	v_mul_f32_e32 v227, v178, v199
	v_cvt_pk_bf16_f32 v192, v219, v220
	v_cvt_pk_bf16_f32 v193, v221, v222
	v_cvt_pk_bf16_f32 v194, v223, v194
	v_cvt_pk_bf16_f32 v195, v200, v195
	ds_read_b128 v[196:199], v231 offset:64
	s_waitcnt lgkmcnt(1)
	v_mfma_f32_16x16x32_bf16 v[22:25], v[22:25], v[188:191], 0
	v_lshlrev_b32_e32 v211, 16, v204
	v_and_b32_e32 v204, 0xffff0000, v204
	v_lshlrev_b32_e32 v216, 16, v205
	v_and_b32_e32 v205, 0xffff0000, v205
	v_lshlrev_b32_e32 v217, 16, v206
	v_and_b32_e32 v206, 0xffff0000, v206
	v_lshlrev_b32_e32 v218, 16, v207
	v_and_b32_e32 v207, 0xffff0000, v207
	v_mul_f32_e32 v201, v171, v201
	v_mul_f32_e32 v208, v173, v208
	v_mul_f32_e32 v209, v175, v209
	v_mul_f32_e32 v210, v177, v210
	v_mul_f32_e32 v228, v180, v204
	v_mul_f32_e32 v229, v182, v205
	v_mul_f32_e32 v230, v184, v206
	v_mul_f32_e32 v232, v186, v207
	v_cvt_pk_bf16_f32 v204, v201, v224
	v_cvt_pk_bf16_f32 v205, v208, v225
	v_cvt_pk_bf16_f32 v206, v209, v226
	v_cvt_pk_bf16_f32 v207, v210, v227
	ds_read_b128 v[188:191], v231 offset:128
	s_waitcnt lgkmcnt(1)
	v_mfma_f32_16x16x32_bf16 v[22:25], v[192:195], v[196:199], v[22:25]
	v_mul_f32_e32 v211, v179, v211
	v_mul_f32_e32 v216, v181, v216
	v_mul_f32_e32 v217, v183, v217
	v_mul_f32_e32 v218, v185, v218
	v_cvt_pk_bf16_f32 v208, v211, v228
	v_cvt_pk_bf16_f32 v209, v216, v229
	v_cvt_pk_bf16_f32 v210, v217, v230
	v_cvt_pk_bf16_f32 v211, v218, v232
	s_waitcnt lgkmcnt(0)
	v_mfma_f32_16x16x32_bf16 v[22:25], v[204:207], v[188:191], v[22:25]
	ds_read_b128 v[188:191], v231 offset:192
	s_add_i32 s8, s8, -2
	s_mov_b32 s0, s1
	s_waitcnt lgkmcnt(0)
	v_mfma_f32_16x16x32_bf16 v[22:25], v[208:211], v[188:191], v[22:25]
	s_cmp_eq_u32 s1, 18
	s_nop 6
	v_pk_fma_f32 v[24:25], v[18:19], v[212:213], v[24:25]
	v_pk_fma_f32 v[22:23], v[20:21], v[214:215], v[22:23]
	s_cbranch_scc0 .LBB0_2531
	s_waitcnt vmcnt(0)
	v_lshlrev_b32_e32 v254, 4, v202
	v_add_u32_e32 v254, 0x14000, v254
	ds_read_b128 v[92:95], v254
	ds_read_b128 v[96:99], v254 offset:8192
	ds_read_b128 v[100:103], v254 offset:16384
	ds_read_b128 v[104:107], v254 offset:24576
	s_waitcnt lgkmcnt(0)
	s_mov_b64 s[0:1], 0
	s_branch .LBB0_2524
